# GEMM K-loops: scalar/address instructions that sat between a block's last MFMA and its barrier moved after the barrier (16 sites)
# speedup vs baseline: 1.0060x; 1.0029x over previous
.LBB0_70:
	s_add_i32 s35, s18, 2
	s_add_u32 s16, s12, 0x100
	s_addc_u32 s17, s13, 0
	s_cmp_lg_u32 s34, s18
	s_cselect_b32 s22, s16, 0
	s_cselect_b32 s23, s17, 0
	s_add_u32 s18, s10, s22
	s_addc_u32 s19, s11, s23
	s_add_i32 s36, 0, 0x10000
	s_add_u32 s22, s8, s22
	s_addc_u32 s23, s9, s23
	v_lshl_add_u64 v[190:191], v[130:131], 0, s[12:13]
	s_add_i32 m0, s3, 0xc000
	ds_read_b128 v[170:173], v153
	ds_read_b128 v[178:181], v153 offset:2048
	ds_read_b128 v[186:189], v153 offset:4096
	ds_read_b128 v[220:223], v153 offset:6144
	ds_read_b128 v[174:177], v153 offset:1024
	ds_read_b128 v[182:185], v153 offset:3072
	ds_read_b128 v[216:219], v153 offset:5120
	ds_read_b128 v[224:227], v153 offset:7168
	global_load_lds_dwordx4 v[190:191], off
	v_lshl_add_u64 v[190:191], v[150:151], 0, s[12:13]
	s_add_i32 m0, s3, 0xe000
	s_nop 0
	global_load_lds_dwordx4 v[190:191], off
	s_waitcnt lgkmcnt(8)
	s_waitcnt vmcnt(10)
	s_barrier
	s_waitcnt lgkmcnt(4)
	v_mfma_f32_16x16x32_bf16 v[124:127], v[154:157], v[170:173], v[124:127]
	v_mfma_f32_16x16x32_bf16 v[120:123], v[162:165], v[170:173], v[120:123]
	v_mfma_f32_16x16x32_bf16 v[116:119], v[154:157], v[178:181], v[116:119]
	v_mfma_f32_16x16x32_bf16 v[108:111], v[162:165], v[178:181], v[108:111]
	v_mfma_f32_16x16x32_bf16 v[100:103], v[154:157], v[186:189], v[100:103]
	v_mfma_f32_16x16x32_bf16 v[92:95], v[162:165], v[186:189], v[92:95]
	v_mfma_f32_16x16x32_bf16 v[84:87], v[154:157], v[220:223], v[84:87]
	v_mfma_f32_16x16x32_bf16 v[76:79], v[162:165], v[220:223], v[76:79]
	s_waitcnt lgkmcnt(0)
	v_mfma_f32_16x16x32_bf16 v[124:127], v[158:161], v[174:177], v[124:127]
	v_mfma_f32_16x16x32_bf16 v[120:123], v[166:169], v[174:177], v[120:123]
	v_mfma_f32_16x16x32_bf16 v[116:119], v[158:161], v[182:185], v[116:119]
	v_mfma_f32_16x16x32_bf16 v[108:111], v[166:169], v[182:185], v[108:111]
	v_mfma_f32_16x16x32_bf16 v[100:103], v[158:161], v[216:219], v[100:103]
	v_mfma_f32_16x16x32_bf16 v[92:95], v[166:169], v[216:219], v[92:95]
	v_mfma_f32_16x16x32_bf16 v[84:87], v[158:161], v[224:227], v[84:87]
	v_mfma_f32_16x16x32_bf16 v[76:79], v[166:169], v[224:227], v[76:79]
	s_barrier
	s_add_i32 s37, 0, 0x14000
	v_add_u32_e32 v190, s37, v152
	s_add_i32 s12, s36, s26
	ds_read_b128 v[228:231], v190
	ds_read_b128 v[236:239], v190 offset:2048
	ds_read_b128 v[232:235], v190 offset:1024
	ds_read_b128 v[240:243], v190 offset:3072
	v_lshl_add_u64 v[190:191], s[22:23], 0, v[132:133]
	s_mov_b32 m0, s12
	v_lshl_add_u64 v[244:245], s[22:23], 0, v[128:129]
	global_load_lds_dwordx4 v132, s[22:23]
	s_add_i32 m0, s12, 0x2000
	s_nop 0
	global_load_lds_dwordx4 v128, s[22:23]
	s_waitcnt vmcnt(10)
	s_barrier
	s_waitcnt lgkmcnt(2)
	v_mfma_f32_16x16x32_bf16 v[112:115], v[228:231], v[170:173], v[112:115]
	v_mfma_f32_16x16x32_bf16 v[104:107], v[236:239], v[170:173], v[104:107]
	v_mfma_f32_16x16x32_bf16 v[96:99], v[228:231], v[178:181], v[96:99]
	v_mfma_f32_16x16x32_bf16 v[88:91], v[236:239], v[178:181], v[88:91]
	v_mfma_f32_16x16x32_bf16 v[80:83], v[228:231], v[186:189], v[80:83]
	v_mfma_f32_16x16x32_bf16 v[72:75], v[236:239], v[186:189], v[72:75]
	v_mfma_f32_16x16x32_bf16 v[68:71], v[228:231], v[220:223], v[68:71]
	v_mfma_f32_16x16x32_bf16 v[64:67], v[236:239], v[220:223], v[64:67]
	s_waitcnt lgkmcnt(0)
	v_mfma_f32_16x16x32_bf16 v[112:115], v[232:235], v[174:177], v[112:115]
	v_mfma_f32_16x16x32_bf16 v[104:107], v[240:243], v[174:177], v[104:107]
	v_mfma_f32_16x16x32_bf16 v[96:99], v[232:235], v[182:185], v[96:99]
	v_mfma_f32_16x16x32_bf16 v[88:91], v[240:243], v[182:185], v[88:91]
	v_mfma_f32_16x16x32_bf16 v[80:83], v[232:235], v[216:219], v[80:83]
	v_mfma_f32_16x16x32_bf16 v[72:75], v[240:243], v[216:219], v[72:75]
	v_mfma_f32_16x16x32_bf16 v[68:71], v[232:235], v[224:227], v[68:71]
	v_mfma_f32_16x16x32_bf16 v[64:67], v[240:243], v[224:227], v[64:67]
	s_barrier
	s_mov_b32 m0, s3
	ds_read_b128 v[170:173], v153 offset:16384
	ds_read_b128 v[178:181], v153 offset:18432
	ds_read_b128 v[186:189], v153 offset:20480
	ds_read_b128 v[220:223], v153 offset:22528
	ds_read_b128 v[174:177], v153 offset:17408
	ds_read_b128 v[182:185], v153 offset:19456
	ds_read_b128 v[216:219], v153 offset:21504
	ds_read_b128 v[224:227], v153 offset:23552
	global_load_lds_dwordx4 v132, s[18:19]
	s_mov_b32 m0, s5
	s_nop 0
	global_load_lds_dwordx4 v128, s[18:19]
	s_waitcnt vmcnt(10)
	s_barrier
	s_waitcnt lgkmcnt(4)
	v_mfma_f32_16x16x32_bf16 v[60:63], v[154:157], v[170:173], v[60:63]
	v_mfma_f32_16x16x32_bf16 v[56:59], v[162:165], v[170:173], v[56:59]
	v_mfma_f32_16x16x32_bf16 v[52:55], v[154:157], v[178:181], v[52:55]
	v_mfma_f32_16x16x32_bf16 v[44:47], v[162:165], v[178:181], v[44:47]
	v_mfma_f32_16x16x32_bf16 v[36:39], v[154:157], v[186:189], v[36:39]
	v_mfma_f32_16x16x32_bf16 v[28:31], v[162:165], v[186:189], v[28:31]
	v_mfma_f32_16x16x32_bf16 v[20:23], v[154:157], v[220:223], v[20:23]
	v_mfma_f32_16x16x32_bf16 v[12:15], v[162:165], v[220:223], v[12:15]
	s_waitcnt lgkmcnt(0)
	v_mfma_f32_16x16x32_bf16 v[60:63], v[158:161], v[174:177], v[60:63]
	v_mfma_f32_16x16x32_bf16 v[56:59], v[166:169], v[174:177], v[56:59]
	v_mfma_f32_16x16x32_bf16 v[52:55], v[158:161], v[182:185], v[52:55]
	v_mfma_f32_16x16x32_bf16 v[44:47], v[166:169], v[182:185], v[44:47]
	v_mfma_f32_16x16x32_bf16 v[36:39], v[158:161], v[216:219], v[36:39]
	v_mfma_f32_16x16x32_bf16 v[28:31], v[166:169], v[216:219], v[28:31]
	v_mfma_f32_16x16x32_bf16 v[20:23], v[158:161], v[224:227], v[20:23]
	v_mfma_f32_16x16x32_bf16 v[12:15], v[166:169], v[224:227], v[12:15]
	s_barrier
	s_add_u32 s12, s22, s25
	s_addc_u32 s13, s23, 0
	s_add_i32 s22, s37, s26
	v_lshl_add_u64 v[250:251], s[12:13], 0, v[132:133]
	s_mov_b32 m0, s22
	v_lshl_add_u64 v[252:253], s[12:13], 0, v[128:129]
	global_load_lds_dwordx4 v132, s[12:13]
	s_add_i32 m0, s22, 0x2000
	s_nop 0
	global_load_lds_dwordx4 v128, s[12:13]
	v_add_u32_e32 v166, 0x18000, v152
	ds_read_b128 v[154:157], v166
	ds_read_b128 v[158:161], v166 offset:1024
	ds_read_b128 v[162:165], v166 offset:2048
	ds_read_b128 v[166:169], v166 offset:3072
	s_waitcnt vmcnt(10)
	s_barrier
	v_mfma_f32_16x16x32_bf16 v[48:51], v[228:231], v[170:173], v[48:51]
	v_mfma_f32_16x16x32_bf16 v[40:43], v[236:239], v[170:173], v[40:43]
	v_mfma_f32_16x16x32_bf16 v[32:35], v[228:231], v[178:181], v[32:35]
	v_mfma_f32_16x16x32_bf16 v[24:27], v[236:239], v[178:181], v[24:27]
	v_mfma_f32_16x16x32_bf16 v[16:19], v[228:231], v[186:189], v[16:19]
	v_mfma_f32_16x16x32_bf16 v[8:11], v[236:239], v[186:189], v[8:11]
	v_mfma_f32_16x16x32_bf16 v[4:7], v[228:231], v[220:223], v[4:7]
	v_mfma_f32_16x16x32_bf16 v[0:3], v[236:239], v[220:223], v[0:3]
	v_mfma_f32_16x16x32_bf16 v[48:51], v[232:235], v[174:177], v[48:51]
	v_mfma_f32_16x16x32_bf16 v[40:43], v[240:243], v[174:177], v[40:43]
	v_mfma_f32_16x16x32_bf16 v[32:35], v[232:235], v[182:185], v[32:35]
	v_mfma_f32_16x16x32_bf16 v[24:27], v[240:243], v[182:185], v[24:27]
	v_mfma_f32_16x16x32_bf16 v[16:19], v[232:235], v[216:219], v[16:19]
	v_mfma_f32_16x16x32_bf16 v[8:11], v[240:243], v[216:219], v[8:11]
	v_mfma_f32_16x16x32_bf16 v[4:7], v[232:235], v[224:227], v[4:7]
	v_mfma_f32_16x16x32_bf16 v[0:3], v[240:243], v[224:227], v[0:3]
	s_barrier
	s_add_i32 s22, 0, 0x18000
	s_add_u32 s12, s18, s25
	s_addc_u32 s13, s19, 0
	s_mov_b32 m0, s27
	ds_read_b128 v[170:173], v153 offset:32768
	ds_read_b128 v[178:181], v153 offset:34816
	ds_read_b128 v[186:189], v153 offset:36864
	ds_read_b128 v[220:223], v153 offset:38912
	ds_read_b128 v[174:177], v153 offset:33792
	ds_read_b128 v[182:185], v153 offset:35840
	ds_read_b128 v[216:219], v153 offset:37888
	ds_read_b128 v[224:227], v153 offset:39936
	global_load_lds_dwordx4 v132, s[12:13]
	s_mov_b32 m0, s28
	s_nop 0
	global_load_lds_dwordx4 v128, s[12:13]
	s_waitcnt lgkmcnt(8)
	s_waitcnt vmcnt(10)
	s_barrier
	s_waitcnt lgkmcnt(4)
	v_mfma_f32_16x16x32_bf16 v[124:127], v[154:157], v[170:173], v[124:127]
	v_mfma_f32_16x16x32_bf16 v[120:123], v[162:165], v[170:173], v[120:123]
	v_mfma_f32_16x16x32_bf16 v[116:119], v[154:157], v[178:181], v[116:119]
	v_mfma_f32_16x16x32_bf16 v[108:111], v[162:165], v[178:181], v[108:111]
	v_mfma_f32_16x16x32_bf16 v[100:103], v[154:157], v[186:189], v[100:103]
	v_mfma_f32_16x16x32_bf16 v[92:95], v[162:165], v[186:189], v[92:95]
	v_mfma_f32_16x16x32_bf16 v[84:87], v[154:157], v[220:223], v[84:87]
	v_mfma_f32_16x16x32_bf16 v[76:79], v[162:165], v[220:223], v[76:79]
	s_waitcnt lgkmcnt(0)
	v_mfma_f32_16x16x32_bf16 v[124:127], v[158:161], v[174:177], v[124:127]
	v_mfma_f32_16x16x32_bf16 v[120:123], v[166:169], v[174:177], v[120:123]
	v_mfma_f32_16x16x32_bf16 v[116:119], v[158:161], v[182:185], v[116:119]
	v_mfma_f32_16x16x32_bf16 v[108:111], v[166:169], v[182:185], v[108:111]
	v_mfma_f32_16x16x32_bf16 v[100:103], v[158:161], v[216:219], v[100:103]
	v_mfma_f32_16x16x32_bf16 v[92:95], v[166:169], v[216:219], v[92:95]
	v_mfma_f32_16x16x32_bf16 v[84:87], v[158:161], v[224:227], v[84:87]
	v_mfma_f32_16x16x32_bf16 v[76:79], v[166:169], v[224:227], v[76:79]
	s_barrier
	s_add_i32 s12, 0, 0x1c000
	s_add_i32 s13, s22, s26
	v_add_u32_e32 v200, s12, v152
	v_lshl_add_u64 v[190:191], v[190:191], 0, s[66:67]
	s_mov_b32 m0, s13
	ds_read_b128 v[228:231], v200
	ds_read_b128 v[236:239], v200 offset:2048
	ds_read_b128 v[232:235], v200 offset:1024
	ds_read_b128 v[240:243], v200 offset:3072
	global_load_lds_dwordx4 v[190:191], off
	v_lshl_add_u64 v[190:191], v[244:245], 0, s[66:67]
	s_add_i32 m0, s13, 0x2000
	s_nop 0
	global_load_lds_dwordx4 v[190:191], off
	s_waitcnt vmcnt(10)
	s_barrier
	s_waitcnt lgkmcnt(2)
	v_mfma_f32_16x16x32_bf16 v[112:115], v[228:231], v[170:173], v[112:115]
	v_mfma_f32_16x16x32_bf16 v[104:107], v[236:239], v[170:173], v[104:107]
	v_mfma_f32_16x16x32_bf16 v[96:99], v[228:231], v[178:181], v[96:99]
	v_mfma_f32_16x16x32_bf16 v[88:91], v[236:239], v[178:181], v[88:91]
	v_mfma_f32_16x16x32_bf16 v[80:83], v[228:231], v[186:189], v[80:83]
	v_mfma_f32_16x16x32_bf16 v[72:75], v[236:239], v[186:189], v[72:75]
	v_mfma_f32_16x16x32_bf16 v[68:71], v[228:231], v[220:223], v[68:71]
	v_mfma_f32_16x16x32_bf16 v[64:67], v[236:239], v[220:223], v[64:67]
	s_waitcnt lgkmcnt(0)
	v_mfma_f32_16x16x32_bf16 v[112:115], v[232:235], v[174:177], v[112:115]
	v_mfma_f32_16x16x32_bf16 v[104:107], v[240:243], v[174:177], v[104:107]
	v_mfma_f32_16x16x32_bf16 v[96:99], v[232:235], v[182:185], v[96:99]
	v_mfma_f32_16x16x32_bf16 v[88:91], v[240:243], v[182:185], v[88:91]
	v_mfma_f32_16x16x32_bf16 v[80:83], v[232:235], v[216:219], v[80:83]
	v_mfma_f32_16x16x32_bf16 v[72:75], v[240:243], v[216:219], v[72:75]
	v_mfma_f32_16x16x32_bf16 v[68:71], v[232:235], v[224:227], v[68:71]
	v_mfma_f32_16x16x32_bf16 v[64:67], v[240:243], v[224:227], v[64:67]
	s_barrier
	s_mov_b32 m0, s30
	ds_read_b128 v[170:173], v153 offset:49152
	ds_read_b128 v[178:181], v153 offset:51200
	ds_read_b128 v[186:189], v153 offset:53248
	ds_read_b128 v[220:223], v153 offset:55296
	ds_read_b128 v[174:177], v153 offset:50176
	ds_read_b128 v[182:185], v153 offset:52224
	ds_read_b128 v[216:219], v153 offset:54272
	ds_read_b128 v[224:227], v153 offset:56320
	s_add_u32 s98, s18, 0x80
	s_addc_u32 s99, s19, 0
	global_load_lds_dwordx4 v132, s[98:99]
	s_mov_b32 m0, s31
	s_nop 0
	global_load_lds_dwordx4 v128, s[98:99]
	s_waitcnt vmcnt(10)
	s_barrier
	s_waitcnt lgkmcnt(4)
	v_mfma_f32_16x16x32_bf16 v[60:63], v[154:157], v[170:173], v[60:63]
	v_mfma_f32_16x16x32_bf16 v[56:59], v[162:165], v[170:173], v[56:59]
	v_mfma_f32_16x16x32_bf16 v[52:55], v[154:157], v[178:181], v[52:55]
	v_mfma_f32_16x16x32_bf16 v[44:47], v[162:165], v[178:181], v[44:47]
	v_mfma_f32_16x16x32_bf16 v[36:39], v[154:157], v[186:189], v[36:39]
	v_mfma_f32_16x16x32_bf16 v[28:31], v[162:165], v[186:189], v[28:31]
	v_mfma_f32_16x16x32_bf16 v[20:23], v[154:157], v[220:223], v[20:23]
	v_mfma_f32_16x16x32_bf16 v[12:15], v[162:165], v[220:223], v[12:15]
	s_waitcnt lgkmcnt(0)
	v_mfma_f32_16x16x32_bf16 v[60:63], v[158:161], v[174:177], v[60:63]
	v_mfma_f32_16x16x32_bf16 v[56:59], v[166:169], v[174:177], v[56:59]
	v_mfma_f32_16x16x32_bf16 v[52:55], v[158:161], v[182:185], v[52:55]
	v_mfma_f32_16x16x32_bf16 v[44:47], v[166:169], v[182:185], v[44:47]
	v_mfma_f32_16x16x32_bf16 v[36:39], v[158:161], v[216:219], v[36:39]
	v_mfma_f32_16x16x32_bf16 v[28:31], v[166:169], v[216:219], v[28:31]
	v_mfma_f32_16x16x32_bf16 v[20:23], v[158:161], v[224:227], v[20:23]
	v_mfma_f32_16x16x32_bf16 v[12:15], v[166:169], v[224:227], v[12:15]
	s_barrier
	s_add_i32 s12, s12, s26
	v_lshl_add_u64 v[154:155], v[250:251], 0, s[66:67]
	s_mov_b32 m0, s12
	s_nop 0
	global_load_lds_dwordx4 v[154:155], off
	v_lshl_add_u64 v[154:155], v[252:253], 0, s[66:67]
	s_add_i32 m0, s12, 0x2000
	s_nop 0
	global_load_lds_dwordx4 v[154:155], off
	v_add_u32_e32 v166, 0x10000, v152
	ds_read_b128 v[154:157], v166
	ds_read_b128 v[158:161], v166 offset:1024
	ds_read_b128 v[162:165], v166 offset:2048
	ds_read_b128 v[166:169], v166 offset:3072
	s_waitcnt vmcnt(10)
	s_barrier
	v_mfma_f32_16x16x32_bf16 v[48:51], v[228:231], v[170:173], v[48:51]
	v_mfma_f32_16x16x32_bf16 v[40:43], v[236:239], v[170:173], v[40:43]
	v_mfma_f32_16x16x32_bf16 v[32:35], v[228:231], v[178:181], v[32:35]
	v_mfma_f32_16x16x32_bf16 v[24:27], v[236:239], v[178:181], v[24:27]
	v_mfma_f32_16x16x32_bf16 v[16:19], v[228:231], v[186:189], v[16:19]
	v_mfma_f32_16x16x32_bf16 v[8:11], v[236:239], v[186:189], v[8:11]
	v_mfma_f32_16x16x32_bf16 v[4:7], v[228:231], v[220:223], v[4:7]
	v_mfma_f32_16x16x32_bf16 v[0:3], v[236:239], v[220:223], v[0:3]
	v_mfma_f32_16x16x32_bf16 v[48:51], v[232:235], v[174:177], v[48:51]
	v_mfma_f32_16x16x32_bf16 v[40:43], v[240:243], v[174:177], v[40:43]
	v_mfma_f32_16x16x32_bf16 v[32:35], v[232:235], v[182:185], v[32:35]
	v_mfma_f32_16x16x32_bf16 v[24:27], v[240:243], v[182:185], v[24:27]
	v_mfma_f32_16x16x32_bf16 v[16:19], v[232:235], v[216:219], v[16:19]
	v_mfma_f32_16x16x32_bf16 v[8:11], v[240:243], v[216:219], v[8:11]
	v_mfma_f32_16x16x32_bf16 v[4:7], v[232:235], v[224:227], v[4:7]
	v_mfma_f32_16x16x32_bf16 v[0:3], v[240:243], v[224:227], v[0:3]
	s_barrier
	s_cmp_ge_u32 s35, s29
	s_mov_b64 s[12:13], s[16:17]
	s_mov_b32 s18, s35
	s_cbranch_scc0 .LBB0_70
	s_waitcnt lgkmcnt(0)
	s_and_b64 s[6:7], s[6:7], exec
	v_mov_b32_e32 v128, v135
	s_mov_b64 s[6:7], s[0:1]
	s_load_dwordx2 s[6:7], s[6:7], 0x88
	s_cselect_b32 s3, 0x2000, 0
	v_readfirstlane_b32 s5, v128
	v_lshrrev_b32_e32 v129, 2, v128
	v_cvt_pk_bf16_f32 v104, v104, v105
	s_waitcnt lgkmcnt(0)
	s_add_u32 s6, s6, 0xfea4400
	s_addc_u32 s7, s7, 0
	s_ashr_i32 s8, s5, 2
	s_andn2_b32 s8, s8, 63
	v_and_or_b32 v128, v128, 15, s8
	s_lshr_b32 s5, s5, 1
	v_lshl_add_u32 v150, s2, 8, v128
	s_lshl_b32 s2, s4, s15
	s_and_b32 s5, s5, 0x60
	s_add_i32 s2, s2, s3
	v_and_or_b32 v132, v129, 12, s5
	v_add_u32_e32 v130, s2, v150
	v_mov_b64_e32 v[128:129], s[6:7]
	v_mad_i64_i32 v[130:131], s[4:5], v130, s96, v[128:129]
	s_lshl_b32 s58, s58, 9
	v_lshl_add_u64 v[130:131], v[130:131], 0, s[58:59]
	v_lshlrev_b32_e32 v132, 1, v132
	v_lshl_add_u64 v[130:131], v[130:131], 0, v[132:133]
	v_cvt_pk_bf16_f32 v105, v106, v107
	global_store_dwordx2 v[130:131], v[104:105], off offset:1824
	v_add3_u32 v104, s2, 16, v150
	v_mad_i64_i32 v[104:105], s[4:5], v104, s96, v[128:129]
	v_lshl_add_u64 v[104:105], v[104:105], 0, s[58:59]
	v_lshl_add_u64 v[104:105], v[104:105], 0, v[132:133]
	v_cvt_pk_bf16_f32 v88, v88, v89
	v_cvt_pk_bf16_f32 v89, v90, v91
	global_store_dwordx2 v[104:105], v[88:89], off offset:1824
	v_add3_u32 v88, s2, 32, v150
	v_mad_i64_i32 v[88:89], s[4:5], v88, s96, v[128:129]
	v_lshl_add_u64 v[88:89], v[88:89], 0, s[58:59]
	v_lshl_add_u64 v[88:89], v[88:89], 0, v[132:133]
	v_cvt_pk_bf16_f32 v72, v72, v73
	v_cvt_pk_bf16_f32 v73, v74, v75
	global_store_dwordx2 v[88:89], v[72:73], off offset:1824
	v_add3_u32 v72, s2, 48, v150
	v_mad_i64_i32 v[72:73], s[4:5], v72, s96, v[128:129]
	v_lshl_add_u64 v[72:73], v[72:73], 0, s[58:59]
	v_lshl_add_u64 v[72:73], v[72:73], 0, v[132:133]
	v_cvt_pk_bf16_f32 v64, v64, v65
	s_add_i32 s3, s2, 0x80
	v_cvt_pk_bf16_f32 v65, v66, v67
	global_store_dwordx2 v[72:73], v[64:65], off offset:1824
	v_add_u32_e32 v64, s3, v150
	v_mad_i64_i32 v[64:65], s[4:5], v64, s96, v[128:129]
	v_lshl_add_u64 v[64:65], v[64:65], 0, s[58:59]
	v_lshl_add_u64 v[64:65], v[64:65], 0, v[132:133]
	v_cvt_pk_bf16_f32 v40, v40, v41
	s_add_i32 s3, s2, 0x90
	v_cvt_pk_bf16_f32 v41, v42, v43
	global_store_dwordx2 v[64:65], v[40:41], off offset:1824
	v_add_u32_e32 v40, s3, v150
	v_mad_i64_i32 v[40:41], s[4:5], v40, s96, v[128:129]
	v_lshl_add_u64 v[40:41], v[40:41], 0, s[58:59]
	v_lshl_add_u64 v[40:41], v[40:41], 0, v[132:133]
	v_cvt_pk_bf16_f32 v24, v24, v25
	s_add_i32 s3, s2, 0xa0
	v_cvt_pk_bf16_f32 v25, v26, v27
	global_store_dwordx2 v[40:41], v[24:25], off offset:1824
	v_add_u32_e32 v24, s3, v150
	v_mad_i64_i32 v[24:25], s[4:5], v24, s96, v[128:129]
	v_lshl_add_u64 v[24:25], v[24:25], 0, s[58:59]
	v_lshl_add_u64 v[24:25], v[24:25], 0, v[132:133]
	v_cvt_pk_bf16_f32 v8, v8, v9
	s_addk_i32 s2, 0xb0
	v_cvt_pk_bf16_f32 v9, v10, v11
	global_store_dwordx2 v[24:25], v[8:9], off offset:1824
	v_add_u32_e32 v8, s2, v150
	v_mad_i64_i32 v[8:9], s[2:3], v8, s96, v[128:129]
	v_lshl_add_u64 v[8:9], v[8:9], 0, s[58:59]
	v_cvt_pk_bf16_f32 v106, v116, v117
	v_cvt_pk_bf16_f32 v107, v118, v119
	v_cvt_pk_bf16_f32 v90, v100, v101
	v_cvt_pk_bf16_f32 v91, v102, v103
	v_cvt_pk_bf16_f32 v74, v84, v85
	v_cvt_pk_bf16_f32 v75, v86, v87
	v_cvt_pk_bf16_f32 v42, v52, v53
	v_cvt_pk_bf16_f32 v43, v54, v55
	v_cvt_pk_bf16_f32 v26, v36, v37
	v_cvt_pk_bf16_f32 v27, v38, v39
	v_lshl_add_u64 v[8:9], v[8:9], 0, v[132:133]
	v_cvt_pk_bf16_f32 v10, v20, v21
	v_cvt_pk_bf16_f32 v11, v22, v23
	v_cvt_pk_bf16_f32 v124, v124, v125
	v_cvt_pk_bf16_f32 v125, v126, v127
	global_store_dwordx2 v[130:131], v[124:125], off offset:1536
	v_cvt_pk_bf16_f32 v120, v120, v121
	v_cvt_pk_bf16_f32 v121, v122, v123
	global_store_dwordx2 v[130:131], v[120:121], off offset:1568
	v_cvt_pk_bf16_f32 v112, v112, v113
	v_cvt_pk_bf16_f32 v113, v114, v115
	global_store_dwordx2 v[130:131], v[112:113], off offset:1792
	global_store_dwordx2 v[104:105], v[106:107], off offset:1536
	v_cvt_pk_bf16_f32 v106, v108, v109
	v_cvt_pk_bf16_f32 v107, v110, v111
	global_store_dwordx2 v[104:105], v[106:107], off offset:1568
	v_cvt_pk_bf16_f32 v96, v96, v97
	v_cvt_pk_bf16_f32 v97, v98, v99
	global_store_dwordx2 v[104:105], v[96:97], off offset:1792
	global_store_dwordx2 v[88:89], v[90:91], off offset:1536
	v_cvt_pk_bf16_f32 v90, v92, v93
	v_cvt_pk_bf16_f32 v91, v94, v95
	global_store_dwordx2 v[88:89], v[90:91], off offset:1568
	v_cvt_pk_bf16_f32 v80, v80, v81
	v_cvt_pk_bf16_f32 v81, v82, v83
	global_store_dwordx2 v[88:89], v[80:81], off offset:1792
	global_store_dwordx2 v[72:73], v[74:75], off offset:1536
	v_cvt_pk_bf16_f32 v74, v76, v77
	v_cvt_pk_bf16_f32 v75, v78, v79
	global_store_dwordx2 v[72:73], v[74:75], off offset:1568
	v_cvt_pk_bf16_f32 v68, v68, v69
	v_cvt_pk_bf16_f32 v69, v70, v71
	global_store_dwordx2 v[72:73], v[68:69], off offset:1792
	v_cvt_pk_bf16_f32 v60, v60, v61
	v_cvt_pk_bf16_f32 v61, v62, v63
	global_store_dwordx2 v[64:65], v[60:61], off offset:1536
	v_cvt_pk_bf16_f32 v56, v56, v57
	v_cvt_pk_bf16_f32 v57, v58, v59
	global_store_dwordx2 v[64:65], v[56:57], off offset:1568
	v_cvt_pk_bf16_f32 v48, v48, v49
	v_cvt_pk_bf16_f32 v49, v50, v51
	global_store_dwordx2 v[64:65], v[48:49], off offset:1792
	global_store_dwordx2 v[40:41], v[42:43], off offset:1536
	v_cvt_pk_bf16_f32 v42, v44, v45
	v_cvt_pk_bf16_f32 v43, v46, v47
	global_store_dwordx2 v[40:41], v[42:43], off offset:1568
	v_cvt_pk_bf16_f32 v32, v32, v33
	v_cvt_pk_bf16_f32 v33, v34, v35
	global_store_dwordx2 v[40:41], v[32:33], off offset:1792
	global_store_dwordx2 v[24:25], v[26:27], off offset:1536
	v_cvt_pk_bf16_f32 v26, v28, v29
	v_cvt_pk_bf16_f32 v27, v30, v31
	global_store_dwordx2 v[24:25], v[26:27], off offset:1568
	v_cvt_pk_bf16_f32 v16, v16, v17
	v_cvt_pk_bf16_f32 v17, v18, v19
	global_store_dwordx2 v[24:25], v[16:17], off offset:1792
	global_store_dwordx2 v[8:9], v[10:11], off offset:1536
	v_cvt_pk_bf16_f32 v10, v12, v13
	v_cvt_pk_bf16_f32 v11, v14, v15
	global_store_dwordx2 v[8:9], v[10:11], off offset:1568
	v_cvt_pk_bf16_f32 v4, v4, v5
	v_cvt_pk_bf16_f32 v5, v6, v7
	global_store_dwordx2 v[8:9], v[4:5], off offset:1792
	v_cvt_pk_bf16_f32 v0, v0, v1
	v_cvt_pk_bf16_f32 v1, v2, v3
	global_store_dwordx2 v[8:9], v[0:1], off offset:1824
	s_waitcnt vmcnt(0)
	s_cmpk_lt_u32 s14, 0x100
	s_cbranch_scc0 .LBB0_73
	s_barrier

.LBB0_145:
	s_add_u32 s6, s2, 0xfffc0080
	s_addc_u32 s7, s3, -1
	s_add_i32 s29, 0, 0x10000
	s_cmp_eq_u32 s28, 12
	s_cselect_b32 s11, s9, s7
	s_cselect_b32 s10, s12, s6
	s_cselect_b32 s7, s13, s27
	s_cselect_b32 s6, s17, s19
	s_add_i32 m0, s50, 0xc000
	ds_read_b128 v[170:173], v216
	ds_read_b128 v[178:181], v216 offset:2048
	ds_read_b128 v[186:189], v216 offset:4096
	ds_read_b128 v[222:225], v216 offset:6144
	ds_read_b128 v[174:177], v216 offset:1024
	ds_read_b128 v[182:185], v216 offset:3072
	ds_read_b128 v[218:221], v216 offset:5120
	ds_read_b128 v[226:229], v216 offset:7168
	global_load_lds_dwordx4 v154, s[2:3]
	s_add_i32 m0, s50, 0xe000
	s_nop 0
	global_load_lds_dwordx4 v156, s[2:3]
	s_waitcnt lgkmcnt(8)
	s_waitcnt vmcnt(10)
	s_barrier
	s_waitcnt lgkmcnt(4)
	v_mfma_f32_16x16x32_bf16 v[124:127], v[128:131], v[170:173], v[124:127]
	v_mfma_f32_16x16x32_bf16 v[120:123], v[162:165], v[170:173], v[120:123]
	v_mfma_f32_16x16x32_bf16 v[108:111], v[128:131], v[178:181], v[108:111]
	v_mfma_f32_16x16x32_bf16 v[104:107], v[162:165], v[178:181], v[104:107]
	v_mfma_f32_16x16x32_bf16 v[92:95], v[128:131], v[186:189], v[92:95]
	v_mfma_f32_16x16x32_bf16 v[88:91], v[162:165], v[186:189], v[88:91]
	v_mfma_f32_16x16x32_bf16 v[76:79], v[128:131], v[222:225], v[76:79]
	v_mfma_f32_16x16x32_bf16 v[72:75], v[162:165], v[222:225], v[72:75]
	s_waitcnt lgkmcnt(0)
	v_mfma_f32_16x16x32_bf16 v[124:127], v[158:161], v[174:177], v[124:127]
	v_mfma_f32_16x16x32_bf16 v[120:123], v[166:169], v[174:177], v[120:123]
	v_mfma_f32_16x16x32_bf16 v[108:111], v[158:161], v[182:185], v[108:111]
	v_mfma_f32_16x16x32_bf16 v[104:107], v[166:169], v[182:185], v[104:107]
	v_mfma_f32_16x16x32_bf16 v[92:95], v[158:161], v[218:221], v[92:95]
	v_mfma_f32_16x16x32_bf16 v[88:91], v[166:169], v[218:221], v[88:91]
	v_mfma_f32_16x16x32_bf16 v[76:79], v[158:161], v[226:229], v[76:79]
	v_mfma_f32_16x16x32_bf16 v[72:75], v[166:169], v[226:229], v[72:75]
	s_barrier
	s_add_i32 s34, 0, 0x14000
	s_add_i32 s29, s29, s15
	v_add_u32_e32 v132, s34, v215
	s_mov_b32 m0, s29
	ds_read_b128 v[230:233], v132
	ds_read_b128 v[238:241], v132 offset:2048
	ds_read_b128 v[234:237], v132 offset:1024
	ds_read_b128 v[242:245], v132 offset:3072
	global_load_lds_dwordx4 v150, s[6:7]
	s_add_i32 m0, s29, 0x2000
	s_nop 0
	global_load_lds_dwordx4 v152, s[6:7]
	s_waitcnt vmcnt(10)
	s_barrier
	s_waitcnt lgkmcnt(2)
	v_mfma_f32_16x16x32_bf16 v[116:119], v[230:233], v[170:173], v[116:119]
	v_mfma_f32_16x16x32_bf16 v[112:115], v[238:241], v[170:173], v[112:115]
	v_mfma_f32_16x16x32_bf16 v[100:103], v[230:233], v[178:181], v[100:103]
	v_mfma_f32_16x16x32_bf16 v[96:99], v[238:241], v[178:181], v[96:99]
	v_mfma_f32_16x16x32_bf16 v[84:87], v[230:233], v[186:189], v[84:87]
	v_mfma_f32_16x16x32_bf16 v[80:83], v[238:241], v[186:189], v[80:83]
	v_mfma_f32_16x16x32_bf16 v[68:71], v[230:233], v[222:225], v[68:71]
	v_mfma_f32_16x16x32_bf16 v[64:67], v[238:241], v[222:225], v[64:67]
	s_waitcnt lgkmcnt(0)
	v_mfma_f32_16x16x32_bf16 v[116:119], v[234:237], v[174:177], v[116:119]
	v_mfma_f32_16x16x32_bf16 v[112:115], v[242:245], v[174:177], v[112:115]
	v_mfma_f32_16x16x32_bf16 v[100:103], v[234:237], v[182:185], v[100:103]
	v_mfma_f32_16x16x32_bf16 v[96:99], v[242:245], v[182:185], v[96:99]
	v_mfma_f32_16x16x32_bf16 v[84:87], v[234:237], v[218:221], v[84:87]
	v_mfma_f32_16x16x32_bf16 v[80:83], v[242:245], v[218:221], v[80:83]
	v_mfma_f32_16x16x32_bf16 v[68:71], v[234:237], v[226:229], v[68:71]
	v_mfma_f32_16x16x32_bf16 v[64:67], v[242:245], v[226:229], v[64:67]
	s_barrier
	s_mov_b32 m0, s50
	v_lshl_add_u64 v[248:249], s[10:11], 0, v[150:151]
	ds_read_b128 v[170:173], v216 offset:16384
	ds_read_b128 v[178:181], v216 offset:18432
	ds_read_b128 v[186:189], v216 offset:20480
	ds_read_b128 v[222:225], v216 offset:22528
	ds_read_b128 v[174:177], v216 offset:17408
	ds_read_b128 v[182:185], v216 offset:19456
	ds_read_b128 v[218:221], v216 offset:21504
	ds_read_b128 v[226:229], v216 offset:23552
	global_load_lds_dwordx4 v150, s[10:11]
	v_lshl_add_u64 v[250:251], s[10:11], 0, v[152:153]
	s_mov_b32 m0, s51
	s_nop 0
	global_load_lds_dwordx4 v152, s[10:11]
	s_waitcnt vmcnt(10)
	s_barrier
	s_waitcnt lgkmcnt(4)
	v_mfma_f32_16x16x32_bf16 v[60:63], v[128:131], v[170:173], v[60:63]
	v_mfma_f32_16x16x32_bf16 v[56:59], v[162:165], v[170:173], v[56:59]
	v_mfma_f32_16x16x32_bf16 v[44:47], v[128:131], v[178:181], v[44:47]
	v_mfma_f32_16x16x32_bf16 v[40:43], v[162:165], v[178:181], v[40:43]
	v_mfma_f32_16x16x32_bf16 v[28:31], v[128:131], v[186:189], v[28:31]
	v_mfma_f32_16x16x32_bf16 v[24:27], v[162:165], v[186:189], v[24:27]
	v_mfma_f32_16x16x32_bf16 v[12:15], v[128:131], v[222:225], v[12:15]
	v_mfma_f32_16x16x32_bf16 v[8:11], v[162:165], v[222:225], v[8:11]
	s_waitcnt lgkmcnt(0)
	v_mfma_f32_16x16x32_bf16 v[60:63], v[158:161], v[174:177], v[60:63]
	v_mfma_f32_16x16x32_bf16 v[56:59], v[166:169], v[174:177], v[56:59]
	v_mfma_f32_16x16x32_bf16 v[44:47], v[158:161], v[182:185], v[44:47]
	v_mfma_f32_16x16x32_bf16 v[40:43], v[166:169], v[182:185], v[40:43]
	v_mfma_f32_16x16x32_bf16 v[28:31], v[158:161], v[218:221], v[28:31]
	v_mfma_f32_16x16x32_bf16 v[24:27], v[166:169], v[218:221], v[24:27]
	v_mfma_f32_16x16x32_bf16 v[12:15], v[158:161], v[226:229], v[12:15]
	v_mfma_f32_16x16x32_bf16 v[8:11], v[166:169], v[226:229], v[8:11]
	s_barrier
	s_add_u32 s30, s6, 0x40000
	s_addc_u32 s31, s7, 0
	s_add_i32 s29, s34, s15
	s_mov_b32 m0, s29
	s_nop 0
	global_load_lds_dwordx4 v150, s[30:31]
	s_add_i32 m0, s29, 0x2000
	s_nop 0
	global_load_lds_dwordx4 v152, s[30:31]
	v_add_u32_e32 v166, 0x18000, v215
	ds_read_b128 v[128:131], v166
	ds_read_b128 v[158:161], v166 offset:1024
	ds_read_b128 v[162:165], v166 offset:2048
	ds_read_b128 v[166:169], v166 offset:3072
	s_waitcnt vmcnt(10)
	s_barrier
	v_mfma_f32_16x16x32_bf16 v[52:55], v[230:233], v[170:173], v[52:55]
	v_mfma_f32_16x16x32_bf16 v[48:51], v[238:241], v[170:173], v[48:51]
	v_mfma_f32_16x16x32_bf16 v[36:39], v[230:233], v[178:181], v[36:39]
	v_mfma_f32_16x16x32_bf16 v[32:35], v[238:241], v[178:181], v[32:35]
	v_mfma_f32_16x16x32_bf16 v[20:23], v[230:233], v[186:189], v[20:23]
	v_mfma_f32_16x16x32_bf16 v[16:19], v[238:241], v[186:189], v[16:19]
	v_mfma_f32_16x16x32_bf16 v[4:7], v[230:233], v[222:225], v[4:7]
	v_mfma_f32_16x16x32_bf16 v[0:3], v[238:241], v[222:225], v[0:3]
	v_mfma_f32_16x16x32_bf16 v[52:55], v[234:237], v[174:177], v[52:55]
	v_mfma_f32_16x16x32_bf16 v[48:51], v[242:245], v[174:177], v[48:51]
	v_mfma_f32_16x16x32_bf16 v[36:39], v[234:237], v[182:185], v[36:39]
	v_mfma_f32_16x16x32_bf16 v[32:35], v[242:245], v[182:185], v[32:35]
	v_mfma_f32_16x16x32_bf16 v[20:23], v[234:237], v[218:221], v[20:23]
	v_mfma_f32_16x16x32_bf16 v[16:19], v[242:245], v[218:221], v[16:19]
	v_mfma_f32_16x16x32_bf16 v[4:7], v[234:237], v[226:229], v[4:7]
	v_mfma_f32_16x16x32_bf16 v[0:3], v[242:245], v[226:229], v[0:3]
	s_barrier
	s_add_i32 s29, 0, 0x18000
	s_add_u32 s10, s10, 0x40000
	s_addc_u32 s11, s11, 0
	s_mov_b32 m0, s36
	ds_read_b128 v[170:173], v216 offset:32768
	ds_read_b128 v[178:181], v216 offset:34816
	ds_read_b128 v[186:189], v216 offset:36864
	ds_read_b128 v[222:225], v216 offset:38912
	ds_read_b128 v[174:177], v216 offset:33792
	ds_read_b128 v[182:185], v216 offset:35840
	ds_read_b128 v[218:221], v216 offset:37888
	ds_read_b128 v[226:229], v216 offset:39936
	global_load_lds_dwordx4 v150, s[10:11]
	s_mov_b32 m0, s37
	s_nop 0
	global_load_lds_dwordx4 v152, s[10:11]
	s_waitcnt lgkmcnt(8)
	s_waitcnt vmcnt(10)
	s_barrier
	s_waitcnt lgkmcnt(4)
	v_mfma_f32_16x16x32_bf16 v[124:127], v[128:131], v[170:173], v[124:127]
	v_mfma_f32_16x16x32_bf16 v[120:123], v[162:165], v[170:173], v[120:123]
	v_mfma_f32_16x16x32_bf16 v[108:111], v[128:131], v[178:181], v[108:111]
	v_mfma_f32_16x16x32_bf16 v[104:107], v[162:165], v[178:181], v[104:107]
	v_mfma_f32_16x16x32_bf16 v[92:95], v[128:131], v[186:189], v[92:95]
	v_mfma_f32_16x16x32_bf16 v[88:91], v[162:165], v[186:189], v[88:91]
	v_mfma_f32_16x16x32_bf16 v[76:79], v[128:131], v[222:225], v[76:79]
	v_mfma_f32_16x16x32_bf16 v[72:75], v[162:165], v[222:225], v[72:75]
	s_waitcnt lgkmcnt(0)
	v_mfma_f32_16x16x32_bf16 v[124:127], v[158:161], v[174:177], v[124:127]
	v_mfma_f32_16x16x32_bf16 v[120:123], v[166:169], v[174:177], v[120:123]
	v_mfma_f32_16x16x32_bf16 v[108:111], v[158:161], v[182:185], v[108:111]
	v_mfma_f32_16x16x32_bf16 v[104:107], v[166:169], v[182:185], v[104:107]
	v_mfma_f32_16x16x32_bf16 v[92:95], v[158:161], v[218:221], v[92:95]
	v_mfma_f32_16x16x32_bf16 v[88:91], v[166:169], v[218:221], v[88:91]
	v_mfma_f32_16x16x32_bf16 v[76:79], v[158:161], v[226:229], v[76:79]
	v_mfma_f32_16x16x32_bf16 v[72:75], v[166:169], v[226:229], v[72:75]
	s_barrier
	s_add_i32 s10, 0, 0x1c000
	s_add_i32 s11, s29, s15
	v_add_u32_e32 v132, s10, v215
	s_mov_b32 m0, s11
	ds_read_b128 v[230:233], v132
	ds_read_b128 v[238:241], v132 offset:2048
	ds_read_b128 v[234:237], v132 offset:1024
	ds_read_b128 v[242:245], v132 offset:3072
	s_add_u32 s98, s6, 0x80
	s_addc_u32 s99, s7, 0
	global_load_lds_dwordx4 v150, s[98:99]
	s_add_i32 m0, s11, 0x2000
	s_nop 0
	global_load_lds_dwordx4 v152, s[98:99]
	s_waitcnt vmcnt(10)
	s_barrier
	s_waitcnt lgkmcnt(2)
	v_mfma_f32_16x16x32_bf16 v[116:119], v[230:233], v[170:173], v[116:119]
	v_mfma_f32_16x16x32_bf16 v[112:115], v[238:241], v[170:173], v[112:115]
	v_mfma_f32_16x16x32_bf16 v[100:103], v[230:233], v[178:181], v[100:103]
	v_mfma_f32_16x16x32_bf16 v[96:99], v[238:241], v[178:181], v[96:99]
	v_mfma_f32_16x16x32_bf16 v[84:87], v[230:233], v[186:189], v[84:87]
	v_mfma_f32_16x16x32_bf16 v[80:83], v[238:241], v[186:189], v[80:83]
	v_mfma_f32_16x16x32_bf16 v[68:71], v[230:233], v[222:225], v[68:71]
	v_mfma_f32_16x16x32_bf16 v[64:67], v[238:241], v[222:225], v[64:67]
	s_waitcnt lgkmcnt(0)
	v_mfma_f32_16x16x32_bf16 v[116:119], v[234:237], v[174:177], v[116:119]
	v_mfma_f32_16x16x32_bf16 v[112:115], v[242:245], v[174:177], v[112:115]
	v_mfma_f32_16x16x32_bf16 v[100:103], v[234:237], v[182:185], v[100:103]
	v_mfma_f32_16x16x32_bf16 v[96:99], v[242:245], v[182:185], v[96:99]
	v_mfma_f32_16x16x32_bf16 v[84:87], v[234:237], v[218:221], v[84:87]
	v_mfma_f32_16x16x32_bf16 v[80:83], v[242:245], v[218:221], v[80:83]
	v_mfma_f32_16x16x32_bf16 v[68:71], v[234:237], v[226:229], v[68:71]
	v_mfma_f32_16x16x32_bf16 v[64:67], v[242:245], v[226:229], v[64:67]
	s_barrier
	s_mov_b32 m0, s52
	v_lshl_add_u64 v[190:191], v[248:249], 0, s[66:67]
	ds_read_b128 v[170:173], v216 offset:49152
	ds_read_b128 v[178:181], v216 offset:51200
	ds_read_b128 v[186:189], v216 offset:53248
	ds_read_b128 v[222:225], v216 offset:55296
	ds_read_b128 v[174:177], v216 offset:50176
	ds_read_b128 v[182:185], v216 offset:52224
	ds_read_b128 v[218:221], v216 offset:54272
	ds_read_b128 v[226:229], v216 offset:56320
	global_load_lds_dwordx4 v[190:191], off
	v_lshl_add_u64 v[190:191], v[250:251], 0, s[66:67]
	s_mov_b32 m0, s53
	s_nop 0
	global_load_lds_dwordx4 v[190:191], off
	s_waitcnt vmcnt(10)
	s_barrier
	s_waitcnt lgkmcnt(4)
	v_mfma_f32_16x16x32_bf16 v[60:63], v[128:131], v[170:173], v[60:63]
	v_mfma_f32_16x16x32_bf16 v[56:59], v[162:165], v[170:173], v[56:59]
	v_mfma_f32_16x16x32_bf16 v[44:47], v[128:131], v[178:181], v[44:47]
	v_mfma_f32_16x16x32_bf16 v[40:43], v[162:165], v[178:181], v[40:43]
	v_mfma_f32_16x16x32_bf16 v[28:31], v[128:131], v[186:189], v[28:31]
	v_mfma_f32_16x16x32_bf16 v[24:27], v[162:165], v[186:189], v[24:27]
	v_mfma_f32_16x16x32_bf16 v[12:15], v[128:131], v[222:225], v[12:15]
	v_mfma_f32_16x16x32_bf16 v[8:11], v[162:165], v[222:225], v[8:11]
	s_waitcnt lgkmcnt(0)
	v_mfma_f32_16x16x32_bf16 v[60:63], v[158:161], v[174:177], v[60:63]
	v_mfma_f32_16x16x32_bf16 v[56:59], v[166:169], v[174:177], v[56:59]
	v_mfma_f32_16x16x32_bf16 v[44:47], v[158:161], v[182:185], v[44:47]
	v_mfma_f32_16x16x32_bf16 v[40:43], v[166:169], v[182:185], v[40:43]
	v_mfma_f32_16x16x32_bf16 v[28:31], v[158:161], v[218:221], v[28:31]
	v_mfma_f32_16x16x32_bf16 v[24:27], v[166:169], v[218:221], v[24:27]
	v_mfma_f32_16x16x32_bf16 v[12:15], v[158:161], v[226:229], v[12:15]
	v_mfma_f32_16x16x32_bf16 v[8:11], v[166:169], v[226:229], v[8:11]
	s_barrier
	s_add_u32 s6, s6, 0x40080
	s_addc_u32 s7, s7, 0
	s_add_i32 s10, s10, s15
	s_mov_b32 m0, s10
	s_nop 0
	global_load_lds_dwordx4 v150, s[6:7]
	s_add_i32 m0, s10, 0x2000
	s_nop 0
	global_load_lds_dwordx4 v152, s[6:7]
	v_add_u32_e32 v166, 0x10000, v215
	ds_read_b128 v[128:131], v166
	ds_read_b128 v[158:161], v166 offset:1024
	ds_read_b128 v[162:165], v166 offset:2048
	ds_read_b128 v[166:169], v166 offset:3072
	s_waitcnt vmcnt(10)
	s_barrier
	v_mfma_f32_16x16x32_bf16 v[52:55], v[230:233], v[170:173], v[52:55]
	v_mfma_f32_16x16x32_bf16 v[48:51], v[238:241], v[170:173], v[48:51]
	v_mfma_f32_16x16x32_bf16 v[36:39], v[230:233], v[178:181], v[36:39]
	v_mfma_f32_16x16x32_bf16 v[32:35], v[238:241], v[178:181], v[32:35]
	v_mfma_f32_16x16x32_bf16 v[20:23], v[230:233], v[186:189], v[20:23]
	v_mfma_f32_16x16x32_bf16 v[16:19], v[238:241], v[186:189], v[16:19]
	v_mfma_f32_16x16x32_bf16 v[4:7], v[230:233], v[222:225], v[4:7]
	v_mfma_f32_16x16x32_bf16 v[0:3], v[238:241], v[222:225], v[0:3]
	v_mfma_f32_16x16x32_bf16 v[52:55], v[234:237], v[174:177], v[52:55]
	v_mfma_f32_16x16x32_bf16 v[48:51], v[242:245], v[174:177], v[48:51]
	v_mfma_f32_16x16x32_bf16 v[36:39], v[234:237], v[182:185], v[36:39]
	v_mfma_f32_16x16x32_bf16 v[32:35], v[242:245], v[182:185], v[32:35]
	v_mfma_f32_16x16x32_bf16 v[20:23], v[234:237], v[218:221], v[20:23]
	v_mfma_f32_16x16x32_bf16 v[16:19], v[242:245], v[218:221], v[16:19]
	v_mfma_f32_16x16x32_bf16 v[4:7], v[234:237], v[226:229], v[4:7]
	v_mfma_f32_16x16x32_bf16 v[0:3], v[242:245], v[226:229], v[0:3]
	s_barrier
	s_add_i32 s28, s28, 2
	s_add_u32 s2, s2, 0x100
	s_addc_u32 s3, s3, 0
	s_add_u32 s19, s19, 0x100
	s_addc_u32 s27, s27, 0
	s_cmp_gt_u32 s28, 13
	s_cbranch_scc0 .LBB0_145
	s_waitcnt lgkmcnt(0)
	v_mov_b32_e32 v166, v135
	s_mov_b64 s[2:3], s[0:1]
	v_readfirstlane_b32 s27, v166
	s_bfe_u32 s19, s27, 0x20006
	s_load_dwordx2 s[30:31], s[2:3], 0x88
	s_mov_b64 s[2:3], s[0:1]
	s_cmp_gt_i32 s8, 31
	s_load_dwordx2 s[28:29], s[2:3], 0x80
	s_cselect_b64 s[6:7], -1, 0
	s_cmp_lt_i32 s8, 32
	s_cselect_b64 s[2:3], -1, 0
	s_ashr_i32 s9, s27, 2
	s_lshl_b32 s8, s8, 8
	s_and_b32 s17, s9, 0xffffffc0
	v_and_b32_e32 v217, 15, v166
	s_add_i32 s17, s17, s8
	v_bfe_u32 v186, v166, 4, 2
	v_or_b32_e32 v158, s17, v217
	s_cmp_gt_i32 s26, 3
	s_mov_b64 s[8:9], -1
	s_cbranch_scc0 .LBB0_829
	s_cmp_gt_u32 s26, 5
	s_cbranch_scc0 .LBB0_409
	s_cmp_gt_u32 s26, 8
	s_cbranch_scc0 .LBB0_406
	s_waitcnt lgkmcnt(0)
	v_and_b32_e32 v128, 1, v166
	v_cmp_eq_u32_e64 s[8:9], 0, v128
	v_cmp_eq_u32_e32 vcc, 1, v128
	s_mov_b32 s10, 0x05040100
	s_mov_b32 s11, 0x07060302
	s_cmp_eq_u32 s6, 0
	s_cbranch_scc1 .Lvf_f_c

.LBB0_1104:
	s_add_u32 s22, s18, 0xfffc0080
	s_addc_u32 s23, s19, -1
	s_add_i32 s47, 0, 0x10000
	s_cmp_eq_u32 s46, 12
	s_cselect_b32 s25, s9, s23
	s_cselect_b32 s24, s42, s22
	s_cselect_b32 s23, s7, s45
	s_cselect_b32 s22, s43, s44
	s_add_i32 m0, s17, 0xc000
	ds_read_b128 v[172:175], v155
	ds_read_b128 v[180:183], v155 offset:2048
	ds_read_b128 v[188:191], v155 offset:4096
	ds_read_b128 v[220:223], v155 offset:6144
	ds_read_b128 v[176:179], v155 offset:1024
	ds_read_b128 v[184:187], v155 offset:3072
	ds_read_b128 v[216:219], v155 offset:5120
	ds_read_b128 v[224:227], v155 offset:7168
	global_load_lds_dwordx4 v130, s[18:19]
	s_add_i32 m0, s17, 0xe000
	s_nop 0
	global_load_lds_dwordx4 v150, s[18:19]
	s_waitcnt lgkmcnt(8)
	s_waitcnt vmcnt(10)
	s_barrier
	s_waitcnt lgkmcnt(4)
	v_mfma_f32_16x16x32_bf16 v[124:127], v[156:159], v[172:175], v[124:127]
	v_mfma_f32_16x16x32_bf16 v[120:123], v[164:167], v[172:175], v[120:123]
	v_mfma_f32_16x16x32_bf16 v[108:111], v[156:159], v[180:183], v[108:111]
	v_mfma_f32_16x16x32_bf16 v[104:107], v[164:167], v[180:183], v[104:107]
	v_mfma_f32_16x16x32_bf16 v[92:95], v[156:159], v[188:191], v[92:95]
	v_mfma_f32_16x16x32_bf16 v[88:91], v[164:167], v[188:191], v[88:91]
	v_mfma_f32_16x16x32_bf16 v[76:79], v[156:159], v[220:223], v[76:79]
	v_mfma_f32_16x16x32_bf16 v[72:75], v[164:167], v[220:223], v[72:75]
	s_waitcnt lgkmcnt(0)
	v_mfma_f32_16x16x32_bf16 v[124:127], v[160:163], v[176:179], v[124:127]
	v_mfma_f32_16x16x32_bf16 v[120:123], v[168:171], v[176:179], v[120:123]
	v_mfma_f32_16x16x32_bf16 v[108:111], v[160:163], v[184:187], v[108:111]
	v_mfma_f32_16x16x32_bf16 v[104:107], v[168:171], v[184:187], v[104:107]
	v_mfma_f32_16x16x32_bf16 v[92:95], v[160:163], v[216:219], v[92:95]
	v_mfma_f32_16x16x32_bf16 v[88:91], v[168:171], v[216:219], v[88:91]
	v_mfma_f32_16x16x32_bf16 v[76:79], v[160:163], v[224:227], v[76:79]
	v_mfma_f32_16x16x32_bf16 v[72:75], v[168:171], v[224:227], v[72:75]
	s_barrier
	s_add_i32 s50, 0, 0x14000
	v_add_u32_e32 v152, s50, v154
	s_add_i32 s47, s47, s29
	ds_read_b128 v[228:231], v152
	ds_read_b128 v[236:239], v152 offset:2048
	ds_read_b128 v[232:235], v152 offset:1024
	ds_read_b128 v[240:243], v152 offset:3072
	s_mov_b32 m0, s47
	s_nop 0
	global_load_lds_dwordx4 v132, s[22:23]
	s_add_i32 m0, s47, 0x2000
	s_nop 0
	global_load_lds_dwordx4 v128, s[22:23]
	s_waitcnt vmcnt(10)
	s_barrier
	s_waitcnt lgkmcnt(2)
	v_mfma_f32_16x16x32_bf16 v[116:119], v[228:231], v[172:175], v[116:119]
	v_mfma_f32_16x16x32_bf16 v[112:115], v[236:239], v[172:175], v[112:115]
	v_mfma_f32_16x16x32_bf16 v[100:103], v[228:231], v[180:183], v[100:103]
	v_mfma_f32_16x16x32_bf16 v[96:99], v[236:239], v[180:183], v[96:99]
	v_mfma_f32_16x16x32_bf16 v[84:87], v[228:231], v[188:191], v[84:87]
	v_mfma_f32_16x16x32_bf16 v[80:83], v[236:239], v[188:191], v[80:83]
	v_mfma_f32_16x16x32_bf16 v[68:71], v[228:231], v[220:223], v[68:71]
	v_mfma_f32_16x16x32_bf16 v[64:67], v[236:239], v[220:223], v[64:67]
	s_waitcnt lgkmcnt(0)
	v_mfma_f32_16x16x32_bf16 v[116:119], v[232:235], v[176:179], v[116:119]
	v_mfma_f32_16x16x32_bf16 v[112:115], v[240:243], v[176:179], v[112:115]
	v_mfma_f32_16x16x32_bf16 v[100:103], v[232:235], v[184:187], v[100:103]
	v_mfma_f32_16x16x32_bf16 v[96:99], v[240:243], v[184:187], v[96:99]
	v_mfma_f32_16x16x32_bf16 v[84:87], v[232:235], v[216:219], v[84:87]
	v_mfma_f32_16x16x32_bf16 v[80:83], v[240:243], v[216:219], v[80:83]
	v_mfma_f32_16x16x32_bf16 v[68:71], v[232:235], v[224:227], v[68:71]
	v_mfma_f32_16x16x32_bf16 v[64:67], v[240:243], v[224:227], v[64:67]
	s_barrier
	s_mov_b32 m0, s17
	v_lshl_add_u64 v[246:247], s[24:25], 0, v[132:133]
	ds_read_b128 v[172:175], v155 offset:16384
	ds_read_b128 v[180:183], v155 offset:18432
	ds_read_b128 v[188:191], v155 offset:20480
	ds_read_b128 v[220:223], v155 offset:22528
	ds_read_b128 v[176:179], v155 offset:17408
	ds_read_b128 v[184:187], v155 offset:19456
	ds_read_b128 v[216:219], v155 offset:21504
	ds_read_b128 v[224:227], v155 offset:23552
	global_load_lds_dwordx4 v132, s[24:25]
	v_lshl_add_u64 v[248:249], s[24:25], 0, v[128:129]
	s_mov_b32 m0, s31
	s_nop 0
	global_load_lds_dwordx4 v128, s[24:25]
	s_waitcnt vmcnt(10)
	s_barrier
	s_waitcnt lgkmcnt(4)
	v_mfma_f32_16x16x32_bf16 v[60:63], v[156:159], v[172:175], v[60:63]
	v_mfma_f32_16x16x32_bf16 v[56:59], v[164:167], v[172:175], v[56:59]
	v_mfma_f32_16x16x32_bf16 v[44:47], v[156:159], v[180:183], v[44:47]
	v_mfma_f32_16x16x32_bf16 v[40:43], v[164:167], v[180:183], v[40:43]
	v_mfma_f32_16x16x32_bf16 v[28:31], v[156:159], v[188:191], v[28:31]
	v_mfma_f32_16x16x32_bf16 v[24:27], v[164:167], v[188:191], v[24:27]
	v_mfma_f32_16x16x32_bf16 v[12:15], v[156:159], v[220:223], v[12:15]
	v_mfma_f32_16x16x32_bf16 v[8:11], v[164:167], v[220:223], v[8:11]
	s_waitcnt lgkmcnt(0)
	v_mfma_f32_16x16x32_bf16 v[60:63], v[160:163], v[176:179], v[60:63]
	v_mfma_f32_16x16x32_bf16 v[56:59], v[168:171], v[176:179], v[56:59]
	v_mfma_f32_16x16x32_bf16 v[44:47], v[160:163], v[184:187], v[44:47]
	v_mfma_f32_16x16x32_bf16 v[40:43], v[168:171], v[184:187], v[40:43]
	v_mfma_f32_16x16x32_bf16 v[28:31], v[160:163], v[216:219], v[28:31]
	v_mfma_f32_16x16x32_bf16 v[24:27], v[168:171], v[216:219], v[24:27]
	v_mfma_f32_16x16x32_bf16 v[12:15], v[160:163], v[224:227], v[12:15]
	v_mfma_f32_16x16x32_bf16 v[8:11], v[168:171], v[224:227], v[8:11]
	s_barrier
	s_add_u32 s48, s22, 0x40000
	s_addc_u32 s49, s23, 0
	s_add_i32 s47, s50, s29
	s_mov_b32 m0, s47
	s_nop 0
	global_load_lds_dwordx4 v132, s[48:49]
	s_add_i32 m0, s47, 0x2000
	s_nop 0
	global_load_lds_dwordx4 v128, s[48:49]
	v_add_u32_e32 v168, 0x18000, v154
	ds_read_b128 v[156:159], v168
	ds_read_b128 v[160:163], v168 offset:1024
	ds_read_b128 v[164:167], v168 offset:2048
	ds_read_b128 v[168:171], v168 offset:3072
	s_waitcnt vmcnt(10)
	s_barrier
	v_mfma_f32_16x16x32_bf16 v[52:55], v[228:231], v[172:175], v[52:55]
	v_mfma_f32_16x16x32_bf16 v[48:51], v[236:239], v[172:175], v[48:51]
	v_mfma_f32_16x16x32_bf16 v[36:39], v[228:231], v[180:183], v[36:39]
	v_mfma_f32_16x16x32_bf16 v[32:35], v[236:239], v[180:183], v[32:35]
	v_mfma_f32_16x16x32_bf16 v[20:23], v[228:231], v[188:191], v[20:23]
	v_mfma_f32_16x16x32_bf16 v[16:19], v[236:239], v[188:191], v[16:19]
	v_mfma_f32_16x16x32_bf16 v[4:7], v[228:231], v[220:223], v[4:7]
	v_mfma_f32_16x16x32_bf16 v[0:3], v[236:239], v[220:223], v[0:3]
	v_mfma_f32_16x16x32_bf16 v[52:55], v[232:235], v[176:179], v[52:55]
	v_mfma_f32_16x16x32_bf16 v[48:51], v[240:243], v[176:179], v[48:51]
	v_mfma_f32_16x16x32_bf16 v[36:39], v[232:235], v[184:187], v[36:39]
	v_mfma_f32_16x16x32_bf16 v[32:35], v[240:243], v[184:187], v[32:35]
	v_mfma_f32_16x16x32_bf16 v[20:23], v[232:235], v[216:219], v[20:23]
	v_mfma_f32_16x16x32_bf16 v[16:19], v[240:243], v[216:219], v[16:19]
	v_mfma_f32_16x16x32_bf16 v[4:7], v[232:235], v[224:227], v[4:7]
	v_mfma_f32_16x16x32_bf16 v[0:3], v[240:243], v[224:227], v[0:3]
	s_barrier
	s_add_i32 s47, 0, 0x18000
	s_add_u32 s24, s24, 0x40000
	s_addc_u32 s25, s25, 0
	s_mov_b32 m0, s34
	ds_read_b128 v[172:175], v155 offset:32768
	ds_read_b128 v[180:183], v155 offset:34816
	ds_read_b128 v[188:191], v155 offset:36864
	ds_read_b128 v[220:223], v155 offset:38912
	ds_read_b128 v[176:179], v155 offset:33792
	ds_read_b128 v[184:187], v155 offset:35840
	ds_read_b128 v[216:219], v155 offset:37888
	ds_read_b128 v[224:227], v155 offset:39936
	global_load_lds_dwordx4 v132, s[24:25]
	s_mov_b32 m0, s35
	s_nop 0
	global_load_lds_dwordx4 v128, s[24:25]
	s_waitcnt lgkmcnt(8)
	s_waitcnt vmcnt(10)
	s_barrier
	s_waitcnt lgkmcnt(4)
	v_mfma_f32_16x16x32_bf16 v[124:127], v[156:159], v[172:175], v[124:127]
	v_mfma_f32_16x16x32_bf16 v[120:123], v[164:167], v[172:175], v[120:123]
	v_mfma_f32_16x16x32_bf16 v[108:111], v[156:159], v[180:183], v[108:111]
	v_mfma_f32_16x16x32_bf16 v[104:107], v[164:167], v[180:183], v[104:107]
	v_mfma_f32_16x16x32_bf16 v[92:95], v[156:159], v[188:191], v[92:95]
	v_mfma_f32_16x16x32_bf16 v[88:91], v[164:167], v[188:191], v[88:91]
	v_mfma_f32_16x16x32_bf16 v[76:79], v[156:159], v[220:223], v[76:79]
	v_mfma_f32_16x16x32_bf16 v[72:75], v[164:167], v[220:223], v[72:75]
	s_waitcnt lgkmcnt(0)
	v_mfma_f32_16x16x32_bf16 v[124:127], v[160:163], v[176:179], v[124:127]
	v_mfma_f32_16x16x32_bf16 v[120:123], v[168:171], v[176:179], v[120:123]
	v_mfma_f32_16x16x32_bf16 v[108:111], v[160:163], v[184:187], v[108:111]
	v_mfma_f32_16x16x32_bf16 v[104:107], v[168:171], v[184:187], v[104:107]
	v_mfma_f32_16x16x32_bf16 v[92:95], v[160:163], v[216:219], v[92:95]
	v_mfma_f32_16x16x32_bf16 v[88:91], v[168:171], v[216:219], v[88:91]
	v_mfma_f32_16x16x32_bf16 v[76:79], v[160:163], v[224:227], v[76:79]
	v_mfma_f32_16x16x32_bf16 v[72:75], v[168:171], v[224:227], v[72:75]
	s_barrier
	s_add_i32 s24, 0, 0x1c000
	s_add_i32 s25, s47, s29
	v_add_u32_e32 v200, s24, v154
	s_mov_b32 m0, s25
	ds_read_b128 v[228:231], v200
	ds_read_b128 v[236:239], v200 offset:2048
	ds_read_b128 v[232:235], v200 offset:1024
	ds_read_b128 v[240:243], v200 offset:3072
	s_add_u32 s98, s22, 0x80
	s_addc_u32 s99, s23, 0
	global_load_lds_dwordx4 v132, s[98:99]
	s_add_i32 m0, s25, 0x2000
	s_nop 0
	global_load_lds_dwordx4 v128, s[98:99]
	s_waitcnt vmcnt(10)
	s_barrier
	s_waitcnt lgkmcnt(2)
	v_mfma_f32_16x16x32_bf16 v[116:119], v[228:231], v[172:175], v[116:119]
	v_mfma_f32_16x16x32_bf16 v[112:115], v[236:239], v[172:175], v[112:115]
	v_mfma_f32_16x16x32_bf16 v[100:103], v[228:231], v[180:183], v[100:103]
	v_mfma_f32_16x16x32_bf16 v[96:99], v[236:239], v[180:183], v[96:99]
	v_mfma_f32_16x16x32_bf16 v[84:87], v[228:231], v[188:191], v[84:87]
	v_mfma_f32_16x16x32_bf16 v[80:83], v[236:239], v[188:191], v[80:83]
	v_mfma_f32_16x16x32_bf16 v[68:71], v[228:231], v[220:223], v[68:71]
	v_mfma_f32_16x16x32_bf16 v[64:67], v[236:239], v[220:223], v[64:67]
	s_waitcnt lgkmcnt(0)
	v_mfma_f32_16x16x32_bf16 v[116:119], v[232:235], v[176:179], v[116:119]
	v_mfma_f32_16x16x32_bf16 v[112:115], v[240:243], v[176:179], v[112:115]
	v_mfma_f32_16x16x32_bf16 v[100:103], v[232:235], v[184:187], v[100:103]
	v_mfma_f32_16x16x32_bf16 v[96:99], v[240:243], v[184:187], v[96:99]
	v_mfma_f32_16x16x32_bf16 v[84:87], v[232:235], v[216:219], v[84:87]
	v_mfma_f32_16x16x32_bf16 v[80:83], v[240:243], v[216:219], v[80:83]
	v_mfma_f32_16x16x32_bf16 v[68:71], v[232:235], v[224:227], v[68:71]
	v_mfma_f32_16x16x32_bf16 v[64:67], v[240:243], v[224:227], v[64:67]
	s_barrier
	s_mov_b32 m0, s36
	v_lshl_add_u64 v[152:153], v[246:247], 0, s[66:67]
	ds_read_b128 v[172:175], v155 offset:49152
	ds_read_b128 v[180:183], v155 offset:51200
	ds_read_b128 v[188:191], v155 offset:53248
	ds_read_b128 v[220:223], v155 offset:55296
	ds_read_b128 v[176:179], v155 offset:50176
	ds_read_b128 v[184:187], v155 offset:52224
	ds_read_b128 v[216:219], v155 offset:54272
	ds_read_b128 v[224:227], v155 offset:56320
	global_load_lds_dwordx4 v[152:153], off
	v_lshl_add_u64 v[152:153], v[248:249], 0, s[66:67]
	s_mov_b32 m0, s37
	s_nop 0
	global_load_lds_dwordx4 v[152:153], off
	s_waitcnt vmcnt(10)
	s_barrier
	s_waitcnt lgkmcnt(4)
	v_mfma_f32_16x16x32_bf16 v[60:63], v[156:159], v[172:175], v[60:63]
	v_mfma_f32_16x16x32_bf16 v[56:59], v[164:167], v[172:175], v[56:59]
	v_mfma_f32_16x16x32_bf16 v[44:47], v[156:159], v[180:183], v[44:47]
	v_mfma_f32_16x16x32_bf16 v[40:43], v[164:167], v[180:183], v[40:43]
	v_mfma_f32_16x16x32_bf16 v[28:31], v[156:159], v[188:191], v[28:31]
	v_mfma_f32_16x16x32_bf16 v[24:27], v[164:167], v[188:191], v[24:27]
	v_mfma_f32_16x16x32_bf16 v[12:15], v[156:159], v[220:223], v[12:15]
	v_mfma_f32_16x16x32_bf16 v[8:11], v[164:167], v[220:223], v[8:11]
	s_waitcnt lgkmcnt(0)
	v_mfma_f32_16x16x32_bf16 v[60:63], v[160:163], v[176:179], v[60:63]
	v_mfma_f32_16x16x32_bf16 v[56:59], v[168:171], v[176:179], v[56:59]
	v_mfma_f32_16x16x32_bf16 v[44:47], v[160:163], v[184:187], v[44:47]
	v_mfma_f32_16x16x32_bf16 v[40:43], v[168:171], v[184:187], v[40:43]
	v_mfma_f32_16x16x32_bf16 v[28:31], v[160:163], v[216:219], v[28:31]
	v_mfma_f32_16x16x32_bf16 v[24:27], v[168:171], v[216:219], v[24:27]
	v_mfma_f32_16x16x32_bf16 v[12:15], v[160:163], v[224:227], v[12:15]
	v_mfma_f32_16x16x32_bf16 v[8:11], v[168:171], v[224:227], v[8:11]
	s_barrier
	s_add_u32 s22, s22, 0x40080
	s_addc_u32 s23, s23, 0
	s_add_i32 s24, s24, s29
	s_mov_b32 m0, s24
	s_nop 0
	global_load_lds_dwordx4 v132, s[22:23]
	s_add_i32 m0, s24, 0x2000
	s_nop 0
	global_load_lds_dwordx4 v128, s[22:23]
	v_add_u32_e32 v168, 0x10000, v154
	ds_read_b128 v[156:159], v168
	ds_read_b128 v[160:163], v168 offset:1024
	ds_read_b128 v[164:167], v168 offset:2048
	ds_read_b128 v[168:171], v168 offset:3072
	s_waitcnt vmcnt(10)
	s_barrier
	v_mfma_f32_16x16x32_bf16 v[52:55], v[228:231], v[172:175], v[52:55]
	v_mfma_f32_16x16x32_bf16 v[48:51], v[236:239], v[172:175], v[48:51]
	v_mfma_f32_16x16x32_bf16 v[36:39], v[228:231], v[180:183], v[36:39]
	v_mfma_f32_16x16x32_bf16 v[32:35], v[236:239], v[180:183], v[32:35]
	v_mfma_f32_16x16x32_bf16 v[20:23], v[228:231], v[188:191], v[20:23]
	v_mfma_f32_16x16x32_bf16 v[16:19], v[236:239], v[188:191], v[16:19]
	v_mfma_f32_16x16x32_bf16 v[4:7], v[228:231], v[220:223], v[4:7]
	v_mfma_f32_16x16x32_bf16 v[0:3], v[236:239], v[220:223], v[0:3]
	v_mfma_f32_16x16x32_bf16 v[52:55], v[232:235], v[176:179], v[52:55]
	v_mfma_f32_16x16x32_bf16 v[48:51], v[240:243], v[176:179], v[48:51]
	v_mfma_f32_16x16x32_bf16 v[36:39], v[232:235], v[184:187], v[36:39]
	v_mfma_f32_16x16x32_bf16 v[32:35], v[240:243], v[184:187], v[32:35]
	v_mfma_f32_16x16x32_bf16 v[20:23], v[232:235], v[216:219], v[20:23]
	v_mfma_f32_16x16x32_bf16 v[16:19], v[240:243], v[216:219], v[16:19]
	v_mfma_f32_16x16x32_bf16 v[4:7], v[232:235], v[224:227], v[4:7]
	v_mfma_f32_16x16x32_bf16 v[0:3], v[240:243], v[224:227], v[0:3]
	s_barrier
	s_add_i32 s46, s46, 2
	s_add_u32 s18, s18, 0x100
	s_addc_u32 s19, s19, 0
	s_add_u32 s44, s44, 0x100
	s_addc_u32 s45, s45, 0
	s_cmp_gt_u32 s46, 13
	s_cbranch_scc0 .LBB0_1104
	s_waitcnt lgkmcnt(0)
	v_mov_b32_e32 v153, v135
	s_mov_b64 s[18:19], s[0:1]
	s_load_dwordx2 s[18:19], s[18:19], 0x88
	s_nop 0
	v_readfirstlane_b32 s7, v153
	s_ashr_i32 s9, s7, 2
	s_lshr_b32 s7, s7, 1
	s_lshl_b32 s22, s41, 7
	s_and_b32 s7, s7, 0x60
	s_andn2_b32 s9, s9, 63
	s_or_b32 s7, s7, s22
	v_lshrrev_b32_e32 v152, 1, v153
	v_and_or_b32 v152, v152, 24, s7
	v_and_or_b32 v153, v153, 15, s9
	v_lshl_add_u32 v156, s16, 8, v153
	v_ashrrev_i32_e32 v153, 31, v152
	v_mov_b32_e32 v168, 0xbfb8aa3b
	v_mov_b32_e32 v169, 0xbfb8aa3b
	v_mov_b32_e32 v170, 1.0
	v_mov_b32_e32 v171, 1.0
	v_pk_mul_f32 v[160:161], v[124:125], v[168:169]
	v_pk_mul_f32 v[162:163], v[126:127], v[168:169]
	v_pk_mul_f32 v[164:165], v[116:117], v[168:169]
	v_pk_mul_f32 v[166:167], v[118:119], v[168:169]
	v_exp_f32_e32 v160, v160
	v_exp_f32_e32 v161, v161
	v_exp_f32_e32 v162, v162
	v_exp_f32_e32 v163, v163
	v_exp_f32_e32 v164, v164
	v_exp_f32_e32 v165, v165
	v_exp_f32_e32 v166, v166
	v_exp_f32_e32 v167, v167
	s_waitcnt lgkmcnt(0)
	v_lshl_add_u64 v[152:153], v[152:153], 1, s[18:19]
	s_mov_b64 s[18:19], 0xa2a4400
	v_lshl_add_u64 v[152:153], v[152:153], 0, s[18:19]
	s_and_b64 vcc, exec, s[4:5]
	s_mov_b32 s41, s6
	s_mov_b32 s16, s8
	s_mov_b64 s[22:23], s[12:13]
	v_pk_add_f32 v[160:161], v[160:161], v[170:171]
	v_pk_add_f32 v[162:163], v[162:163], v[170:171]
	v_pk_add_f32 v[164:165], v[164:165], v[170:171]
	v_pk_add_f32 v[166:167], v[166:167], v[170:171]
	v_rcp_f32_e32 v160, v160
	v_rcp_f32_e32 v161, v161
	v_rcp_f32_e32 v162, v162
	v_rcp_f32_e32 v163, v163
	v_rcp_f32_e32 v164, v164
	v_rcp_f32_e32 v165, v165
	v_rcp_f32_e32 v166, v166
	v_rcp_f32_e32 v167, v167
	v_mov_b32_e32 v158, v156
	v_mad_i64_i32 v[158:159], s[18:19], v158, s73, v[152:153]
	v_pk_mul_f32 v[124:125], v[124:125], v[160:161]
	v_pk_mul_f32 v[126:127], v[126:127], v[162:163]
	v_pk_mul_f32 v[116:117], v[116:117], v[164:165]
	v_pk_mul_f32 v[118:119], v[118:119], v[166:167]
	v_pk_mul_f32 v[120:121], v[120:121], v[124:125]
	v_pk_mul_f32 v[122:123], v[122:123], v[126:127]
	v_pk_mul_f32 v[112:113], v[112:113], v[116:117]
	v_pk_mul_f32 v[114:115], v[114:115], v[118:119]
	v_cvt_pk_bf16_f32 v120, v120, v121
	v_cvt_pk_bf16_f32 v121, v122, v123
	v_cvt_pk_bf16_f32 v122, v112, v113
	v_cvt_pk_bf16_f32 v123, v114, v115
	global_store_dwordx4 v[158:159], v[120:123], off sc1
	v_pk_mul_f32 v[160:161], v[108:109], v[168:169]
	v_pk_mul_f32 v[162:163], v[110:111], v[168:169]
	v_pk_mul_f32 v[164:165], v[100:101], v[168:169]
	v_pk_mul_f32 v[166:167], v[102:103], v[168:169]
	v_exp_f32_e32 v160, v160
	v_exp_f32_e32 v161, v161
	v_exp_f32_e32 v162, v162
	v_exp_f32_e32 v163, v163
	v_exp_f32_e32 v164, v164
	v_exp_f32_e32 v165, v165
	v_exp_f32_e32 v166, v166
	v_exp_f32_e32 v167, v167
	v_pk_add_f32 v[160:161], v[160:161], v[170:171]
	v_pk_add_f32 v[162:163], v[162:163], v[170:171]
	v_pk_add_f32 v[164:165], v[164:165], v[170:171]
	v_pk_add_f32 v[166:167], v[166:167], v[170:171]
	v_rcp_f32_e32 v160, v160
	v_rcp_f32_e32 v161, v161
	v_rcp_f32_e32 v162, v162
	v_rcp_f32_e32 v163, v163
	v_rcp_f32_e32 v164, v164
	v_rcp_f32_e32 v165, v165
	v_rcp_f32_e32 v166, v166
	v_rcp_f32_e32 v167, v167
	v_add_u32_e32 v158, 0x10, v156
	v_mad_i64_i32 v[158:159], s[18:19], v158, s73, v[152:153]
	v_pk_mul_f32 v[108:109], v[108:109], v[160:161]
	v_pk_mul_f32 v[110:111], v[110:111], v[162:163]
	v_pk_mul_f32 v[100:101], v[100:101], v[164:165]
	v_pk_mul_f32 v[102:103], v[102:103], v[166:167]
	v_pk_mul_f32 v[104:105], v[104:105], v[108:109]
	v_pk_mul_f32 v[106:107], v[106:107], v[110:111]
	v_pk_mul_f32 v[96:97], v[96:97], v[100:101]
	v_pk_mul_f32 v[98:99], v[98:99], v[102:103]
	v_cvt_pk_bf16_f32 v104, v104, v105
	v_cvt_pk_bf16_f32 v105, v106, v107
	v_cvt_pk_bf16_f32 v106, v96, v97
	v_cvt_pk_bf16_f32 v107, v98, v99
	global_store_dwordx4 v[158:159], v[104:107], off sc1
	v_pk_mul_f32 v[160:161], v[92:93], v[168:169]
	v_pk_mul_f32 v[162:163], v[94:95], v[168:169]
	v_pk_mul_f32 v[164:165], v[84:85], v[168:169]
	v_pk_mul_f32 v[166:167], v[86:87], v[168:169]
	v_exp_f32_e32 v160, v160
	v_exp_f32_e32 v161, v161
	v_exp_f32_e32 v162, v162
	v_exp_f32_e32 v163, v163
	v_exp_f32_e32 v164, v164
	v_exp_f32_e32 v165, v165
	v_exp_f32_e32 v166, v166
	v_exp_f32_e32 v167, v167
	v_pk_add_f32 v[160:161], v[160:161], v[170:171]
	v_pk_add_f32 v[162:163], v[162:163], v[170:171]
	v_pk_add_f32 v[164:165], v[164:165], v[170:171]
	v_pk_add_f32 v[166:167], v[166:167], v[170:171]
	v_rcp_f32_e32 v160, v160
	v_rcp_f32_e32 v161, v161
	v_rcp_f32_e32 v162, v162
	v_rcp_f32_e32 v163, v163
	v_rcp_f32_e32 v164, v164
	v_rcp_f32_e32 v165, v165
	v_rcp_f32_e32 v166, v166
	v_rcp_f32_e32 v167, v167
	v_add_u32_e32 v158, 0x20, v156
	v_mad_i64_i32 v[158:159], s[18:19], v158, s73, v[152:153]
	v_pk_mul_f32 v[92:93], v[92:93], v[160:161]
	v_pk_mul_f32 v[94:95], v[94:95], v[162:163]
	v_pk_mul_f32 v[84:85], v[84:85], v[164:165]
	v_pk_mul_f32 v[86:87], v[86:87], v[166:167]
	v_pk_mul_f32 v[88:89], v[88:89], v[92:93]
	v_pk_mul_f32 v[90:91], v[90:91], v[94:95]
	v_pk_mul_f32 v[80:81], v[80:81], v[84:85]
	v_pk_mul_f32 v[82:83], v[82:83], v[86:87]
	v_cvt_pk_bf16_f32 v88, v88, v89
	v_cvt_pk_bf16_f32 v89, v90, v91
	v_cvt_pk_bf16_f32 v90, v80, v81
	v_cvt_pk_bf16_f32 v91, v82, v83
	global_store_dwordx4 v[158:159], v[88:91], off sc1
	v_pk_mul_f32 v[160:161], v[76:77], v[168:169]
	v_pk_mul_f32 v[162:163], v[78:79], v[168:169]
	v_pk_mul_f32 v[164:165], v[68:69], v[168:169]
	v_pk_mul_f32 v[166:167], v[70:71], v[168:169]
	v_exp_f32_e32 v160, v160
	v_exp_f32_e32 v161, v161
	v_exp_f32_e32 v162, v162
	v_exp_f32_e32 v163, v163
	v_exp_f32_e32 v164, v164
	v_exp_f32_e32 v165, v165
	v_exp_f32_e32 v166, v166
	v_exp_f32_e32 v167, v167
	v_pk_add_f32 v[160:161], v[160:161], v[170:171]
	v_pk_add_f32 v[162:163], v[162:163], v[170:171]
	v_pk_add_f32 v[164:165], v[164:165], v[170:171]
	v_pk_add_f32 v[166:167], v[166:167], v[170:171]
	v_rcp_f32_e32 v160, v160
	v_rcp_f32_e32 v161, v161
	v_rcp_f32_e32 v162, v162
	v_rcp_f32_e32 v163, v163
	v_rcp_f32_e32 v164, v164
	v_rcp_f32_e32 v165, v165
	v_rcp_f32_e32 v166, v166
	v_rcp_f32_e32 v167, v167
	v_add_u32_e32 v158, 0x30, v156
	v_mad_i64_i32 v[158:159], s[18:19], v158, s73, v[152:153]
	v_pk_mul_f32 v[76:77], v[76:77], v[160:161]
	v_pk_mul_f32 v[78:79], v[78:79], v[162:163]
	v_pk_mul_f32 v[68:69], v[68:69], v[164:165]
	v_pk_mul_f32 v[70:71], v[70:71], v[166:167]
	v_pk_mul_f32 v[72:73], v[72:73], v[76:77]
	v_pk_mul_f32 v[74:75], v[74:75], v[78:79]
	v_pk_mul_f32 v[64:65], v[64:65], v[68:69]
	v_pk_mul_f32 v[66:67], v[66:67], v[70:71]
	v_cvt_pk_bf16_f32 v72, v72, v73
	v_cvt_pk_bf16_f32 v73, v74, v75
	v_cvt_pk_bf16_f32 v74, v64, v65
	v_cvt_pk_bf16_f32 v75, v66, v67
	global_store_dwordx4 v[158:159], v[72:75], off sc1
	v_pk_mul_f32 v[160:161], v[60:61], v[168:169]
	v_pk_mul_f32 v[162:163], v[62:63], v[168:169]
	v_pk_mul_f32 v[164:165], v[52:53], v[168:169]
	v_pk_mul_f32 v[166:167], v[54:55], v[168:169]
	v_exp_f32_e32 v160, v160
	v_exp_f32_e32 v161, v161
	v_exp_f32_e32 v162, v162
	v_exp_f32_e32 v163, v163
	v_exp_f32_e32 v164, v164
	v_exp_f32_e32 v165, v165
	v_exp_f32_e32 v166, v166
	v_exp_f32_e32 v167, v167
	v_pk_add_f32 v[160:161], v[160:161], v[170:171]
	v_pk_add_f32 v[162:163], v[162:163], v[170:171]
	v_pk_add_f32 v[164:165], v[164:165], v[170:171]
	v_pk_add_f32 v[166:167], v[166:167], v[170:171]
	v_rcp_f32_e32 v160, v160
	v_rcp_f32_e32 v161, v161
	v_rcp_f32_e32 v162, v162
	v_rcp_f32_e32 v163, v163
	v_rcp_f32_e32 v164, v164
	v_rcp_f32_e32 v165, v165
	v_rcp_f32_e32 v166, v166
	v_rcp_f32_e32 v167, v167
	v_add_u32_e32 v158, 0x80, v156
	v_mad_i64_i32 v[158:159], s[18:19], v158, s73, v[152:153]
	v_pk_mul_f32 v[60:61], v[60:61], v[160:161]
	v_pk_mul_f32 v[62:63], v[62:63], v[162:163]
	v_pk_mul_f32 v[52:53], v[52:53], v[164:165]
	v_pk_mul_f32 v[54:55], v[54:55], v[166:167]
	v_pk_mul_f32 v[56:57], v[56:57], v[60:61]
	v_pk_mul_f32 v[58:59], v[58:59], v[62:63]
	v_pk_mul_f32 v[48:49], v[48:49], v[52:53]
	v_pk_mul_f32 v[50:51], v[50:51], v[54:55]
	v_cvt_pk_bf16_f32 v56, v56, v57
	v_cvt_pk_bf16_f32 v57, v58, v59
	v_cvt_pk_bf16_f32 v58, v48, v49
	v_cvt_pk_bf16_f32 v59, v50, v51
	global_store_dwordx4 v[158:159], v[56:59], off sc1
	v_pk_mul_f32 v[160:161], v[44:45], v[168:169]
	v_pk_mul_f32 v[162:163], v[46:47], v[168:169]
	v_pk_mul_f32 v[164:165], v[36:37], v[168:169]
	v_pk_mul_f32 v[166:167], v[38:39], v[168:169]
	v_exp_f32_e32 v160, v160
	v_exp_f32_e32 v161, v161
	v_exp_f32_e32 v162, v162
	v_exp_f32_e32 v163, v163
	v_exp_f32_e32 v164, v164
	v_exp_f32_e32 v165, v165
	v_exp_f32_e32 v166, v166
	v_exp_f32_e32 v167, v167
	v_pk_add_f32 v[160:161], v[160:161], v[170:171]
	v_pk_add_f32 v[162:163], v[162:163], v[170:171]
	v_pk_add_f32 v[164:165], v[164:165], v[170:171]
	v_pk_add_f32 v[166:167], v[166:167], v[170:171]
	v_rcp_f32_e32 v160, v160
	v_rcp_f32_e32 v161, v161
	v_rcp_f32_e32 v162, v162
	v_rcp_f32_e32 v163, v163
	v_rcp_f32_e32 v164, v164
	v_rcp_f32_e32 v165, v165
	v_rcp_f32_e32 v166, v166
	v_rcp_f32_e32 v167, v167
	v_add_u32_e32 v158, 0x90, v156
	v_mad_i64_i32 v[158:159], s[18:19], v158, s73, v[152:153]
	v_pk_mul_f32 v[44:45], v[44:45], v[160:161]
	v_pk_mul_f32 v[46:47], v[46:47], v[162:163]
	v_pk_mul_f32 v[36:37], v[36:37], v[164:165]
	v_pk_mul_f32 v[38:39], v[38:39], v[166:167]
	v_pk_mul_f32 v[40:41], v[40:41], v[44:45]
	v_pk_mul_f32 v[42:43], v[42:43], v[46:47]
	v_pk_mul_f32 v[32:33], v[32:33], v[36:37]
	v_pk_mul_f32 v[34:35], v[34:35], v[38:39]
	v_cvt_pk_bf16_f32 v40, v40, v41
	v_cvt_pk_bf16_f32 v41, v42, v43
	v_cvt_pk_bf16_f32 v42, v32, v33
	v_cvt_pk_bf16_f32 v43, v34, v35
	global_store_dwordx4 v[158:159], v[40:43], off sc1
	v_pk_mul_f32 v[160:161], v[28:29], v[168:169]
	v_pk_mul_f32 v[162:163], v[30:31], v[168:169]
	v_pk_mul_f32 v[164:165], v[20:21], v[168:169]
	v_pk_mul_f32 v[166:167], v[22:23], v[168:169]
	v_exp_f32_e32 v160, v160
	v_exp_f32_e32 v161, v161
	v_exp_f32_e32 v162, v162
	v_exp_f32_e32 v163, v163
	v_exp_f32_e32 v164, v164
	v_exp_f32_e32 v165, v165
	v_exp_f32_e32 v166, v166
	v_exp_f32_e32 v167, v167
	v_pk_add_f32 v[160:161], v[160:161], v[170:171]
	v_pk_add_f32 v[162:163], v[162:163], v[170:171]
	v_pk_add_f32 v[164:165], v[164:165], v[170:171]
	v_pk_add_f32 v[166:167], v[166:167], v[170:171]
	v_rcp_f32_e32 v160, v160
	v_rcp_f32_e32 v161, v161
	v_rcp_f32_e32 v162, v162
	v_rcp_f32_e32 v163, v163
	v_rcp_f32_e32 v164, v164
	v_rcp_f32_e32 v165, v165
	v_rcp_f32_e32 v166, v166
	v_rcp_f32_e32 v167, v167
	v_add_u32_e32 v158, 0xa0, v156
	v_mad_i64_i32 v[158:159], s[18:19], v158, s73, v[152:153]
	v_pk_mul_f32 v[28:29], v[28:29], v[160:161]
	v_pk_mul_f32 v[30:31], v[30:31], v[162:163]
	v_pk_mul_f32 v[20:21], v[20:21], v[164:165]
	v_pk_mul_f32 v[22:23], v[22:23], v[166:167]
	v_pk_mul_f32 v[24:25], v[24:25], v[28:29]
	v_pk_mul_f32 v[26:27], v[26:27], v[30:31]
	v_pk_mul_f32 v[16:17], v[16:17], v[20:21]
	v_pk_mul_f32 v[18:19], v[18:19], v[22:23]
	v_cvt_pk_bf16_f32 v24, v24, v25
	v_cvt_pk_bf16_f32 v25, v26, v27
	v_cvt_pk_bf16_f32 v26, v16, v17
	v_cvt_pk_bf16_f32 v27, v18, v19
	global_store_dwordx4 v[158:159], v[24:27], off sc1
	v_pk_mul_f32 v[160:161], v[12:13], v[168:169]
	v_pk_mul_f32 v[162:163], v[14:15], v[168:169]
	v_pk_mul_f32 v[164:165], v[4:5], v[168:169]
	v_pk_mul_f32 v[166:167], v[6:7], v[168:169]
	v_exp_f32_e32 v160, v160
	v_exp_f32_e32 v161, v161
	v_exp_f32_e32 v162, v162
	v_exp_f32_e32 v163, v163
	v_exp_f32_e32 v164, v164
	v_exp_f32_e32 v165, v165
	v_exp_f32_e32 v166, v166
	v_exp_f32_e32 v167, v167
	v_pk_add_f32 v[160:161], v[160:161], v[170:171]
	v_pk_add_f32 v[162:163], v[162:163], v[170:171]
	v_pk_add_f32 v[164:165], v[164:165], v[170:171]
	v_pk_add_f32 v[166:167], v[166:167], v[170:171]
	v_rcp_f32_e32 v160, v160
	v_rcp_f32_e32 v161, v161
	v_rcp_f32_e32 v162, v162
	v_rcp_f32_e32 v163, v163
	v_rcp_f32_e32 v164, v164
	v_rcp_f32_e32 v165, v165
	v_rcp_f32_e32 v166, v166
	v_rcp_f32_e32 v167, v167
	v_add_u32_e32 v158, 0xb0, v156
	v_mad_i64_i32 v[158:159], s[18:19], v158, s73, v[152:153]
	v_pk_mul_f32 v[12:13], v[12:13], v[160:161]
	v_pk_mul_f32 v[14:15], v[14:15], v[162:163]
	v_pk_mul_f32 v[4:5], v[4:5], v[164:165]
	v_pk_mul_f32 v[6:7], v[6:7], v[166:167]
	v_pk_mul_f32 v[8:9], v[8:9], v[12:13]
	v_pk_mul_f32 v[10:11], v[10:11], v[14:15]
	v_pk_mul_f32 v[0:1], v[0:1], v[4:5]
	v_pk_mul_f32 v[2:3], v[2:3], v[6:7]
	v_cvt_pk_bf16_f32 v8, v8, v9
	v_cvt_pk_bf16_f32 v9, v10, v11
	v_cvt_pk_bf16_f32 v10, v0, v1
	v_cvt_pk_bf16_f32 v11, v2, v3
	global_store_dwordx4 v[158:159], v[8:11], off sc1
	s_mov_b64 s[18:19], s[10:11]
	s_cbranch_vccz .LBB0_1101
	s_waitcnt vmcnt(0)
	s_cmpk_gt_u32 s14, 0xff
	s_cbranch_scc1 .LBB0_1108
	s_barrier

.LBB0_1234:
	s_add_i32 s40, s10, 2
	s_add_u32 s12, s8, 0x80
	s_addc_u32 s11, s9, 0
	s_add_i32 s41, 0, 0x10000
	s_cmp_eq_u32 s29, s10
	s_cselect_b32 s10, s2, s12
	s_cselect_b32 s11, s3, s11
	s_cselect_b32 s13, s7, s39
	s_cselect_b32 s12, s6, s38
	s_add_i32 m0, s22, 0xc000
	ds_read_b128 v[172:175], v155
	ds_read_b128 v[180:183], v155 offset:2048
	ds_read_b128 v[188:191], v155 offset:4096
	ds_read_b128 v[220:223], v155 offset:6144
	ds_read_b128 v[176:179], v155 offset:1024
	ds_read_b128 v[184:187], v155 offset:3072
	ds_read_b128 v[216:219], v155 offset:5120
	ds_read_b128 v[224:227], v155 offset:7168
	global_load_lds_dwordx4 v130, s[8:9]
	s_add_i32 m0, s22, 0xe000
	s_nop 0
	global_load_lds_dwordx4 v150, s[8:9]
	s_waitcnt lgkmcnt(8)
	s_waitcnt vmcnt(10)
	s_barrier
	s_waitcnt lgkmcnt(4)
	v_mfma_f32_16x16x32_bf16 v[124:127], v[156:159], v[172:175], v[124:127]
	v_mfma_f32_16x16x32_bf16 v[120:123], v[164:167], v[172:175], v[120:123]
	v_mfma_f32_16x16x32_bf16 v[116:119], v[156:159], v[180:183], v[116:119]
	v_mfma_f32_16x16x32_bf16 v[108:111], v[164:167], v[180:183], v[108:111]
	v_mfma_f32_16x16x32_bf16 v[100:103], v[156:159], v[188:191], v[100:103]
	v_mfma_f32_16x16x32_bf16 v[92:95], v[164:167], v[188:191], v[92:95]
	v_mfma_f32_16x16x32_bf16 v[84:87], v[156:159], v[220:223], v[84:87]
	v_mfma_f32_16x16x32_bf16 v[76:79], v[164:167], v[220:223], v[76:79]
	s_waitcnt lgkmcnt(0)
	v_mfma_f32_16x16x32_bf16 v[124:127], v[160:163], v[176:179], v[124:127]
	v_mfma_f32_16x16x32_bf16 v[120:123], v[168:171], v[176:179], v[120:123]
	v_mfma_f32_16x16x32_bf16 v[116:119], v[160:163], v[184:187], v[116:119]
	v_mfma_f32_16x16x32_bf16 v[108:111], v[168:171], v[184:187], v[108:111]
	v_mfma_f32_16x16x32_bf16 v[100:103], v[160:163], v[216:219], v[100:103]
	v_mfma_f32_16x16x32_bf16 v[92:95], v[168:171], v[216:219], v[92:95]
	v_mfma_f32_16x16x32_bf16 v[84:87], v[160:163], v[224:227], v[84:87]
	v_mfma_f32_16x16x32_bf16 v[76:79], v[168:171], v[224:227], v[76:79]
	s_barrier
	s_add_i32 s42, 0, 0x14000
	v_add_u32_e32 v152, s42, v154
	s_add_i32 s41, s41, s19
	ds_read_b128 v[228:231], v152
	ds_read_b128 v[236:239], v152 offset:2048
	ds_read_b128 v[232:235], v152 offset:1024
	ds_read_b128 v[240:243], v152 offset:3072
	v_lshl_add_u64 v[152:153], s[12:13], 0, v[132:133]
	s_mov_b32 m0, s41
	v_lshl_add_u64 v[244:245], s[12:13], 0, v[128:129]
	global_load_lds_dwordx4 v132, s[12:13]
	s_add_i32 m0, s41, 0x2000
	s_nop 0
	global_load_lds_dwordx4 v128, s[12:13]
	s_waitcnt vmcnt(10)
	s_barrier
	s_waitcnt lgkmcnt(2)
	v_mfma_f32_16x16x32_bf16 v[112:115], v[228:231], v[172:175], v[112:115]
	v_mfma_f32_16x16x32_bf16 v[104:107], v[236:239], v[172:175], v[104:107]
	v_mfma_f32_16x16x32_bf16 v[96:99], v[228:231], v[180:183], v[96:99]
	v_mfma_f32_16x16x32_bf16 v[88:91], v[236:239], v[180:183], v[88:91]
	v_mfma_f32_16x16x32_bf16 v[80:83], v[228:231], v[188:191], v[80:83]
	v_mfma_f32_16x16x32_bf16 v[72:75], v[236:239], v[188:191], v[72:75]
	v_mfma_f32_16x16x32_bf16 v[68:71], v[228:231], v[220:223], v[68:71]
	v_mfma_f32_16x16x32_bf16 v[64:67], v[236:239], v[220:223], v[64:67]
	s_waitcnt lgkmcnt(0)
	v_mfma_f32_16x16x32_bf16 v[112:115], v[232:235], v[176:179], v[112:115]
	v_mfma_f32_16x16x32_bf16 v[104:107], v[240:243], v[176:179], v[104:107]
	v_mfma_f32_16x16x32_bf16 v[96:99], v[232:235], v[184:187], v[96:99]
	v_mfma_f32_16x16x32_bf16 v[88:91], v[240:243], v[184:187], v[88:91]
	v_mfma_f32_16x16x32_bf16 v[80:83], v[232:235], v[216:219], v[80:83]
	v_mfma_f32_16x16x32_bf16 v[72:75], v[240:243], v[216:219], v[72:75]
	v_mfma_f32_16x16x32_bf16 v[68:71], v[232:235], v[224:227], v[68:71]
	v_mfma_f32_16x16x32_bf16 v[64:67], v[240:243], v[224:227], v[64:67]
	s_barrier
	s_mov_b32 m0, s22
	v_lshl_add_u64 v[246:247], s[10:11], 0, v[132:133]
	ds_read_b128 v[172:175], v155 offset:16384
	ds_read_b128 v[180:183], v155 offset:18432
	ds_read_b128 v[188:191], v155 offset:20480
	ds_read_b128 v[220:223], v155 offset:22528
	ds_read_b128 v[176:179], v155 offset:17408
	ds_read_b128 v[184:187], v155 offset:19456
	ds_read_b128 v[216:219], v155 offset:21504
	ds_read_b128 v[224:227], v155 offset:23552
	global_load_lds_dwordx4 v132, s[10:11]
	v_lshl_add_u64 v[248:249], s[10:11], 0, v[128:129]
	s_mov_b32 m0, s23
	s_nop 0
	global_load_lds_dwordx4 v128, s[10:11]
	s_waitcnt vmcnt(10)
	s_barrier
	s_waitcnt lgkmcnt(4)
	v_mfma_f32_16x16x32_bf16 v[60:63], v[156:159], v[172:175], v[60:63]
	v_mfma_f32_16x16x32_bf16 v[56:59], v[164:167], v[172:175], v[56:59]
	v_mfma_f32_16x16x32_bf16 v[52:55], v[156:159], v[180:183], v[52:55]
	v_mfma_f32_16x16x32_bf16 v[44:47], v[164:167], v[180:183], v[44:47]
	v_mfma_f32_16x16x32_bf16 v[36:39], v[156:159], v[188:191], v[36:39]
	v_mfma_f32_16x16x32_bf16 v[28:31], v[164:167], v[188:191], v[28:31]
	v_mfma_f32_16x16x32_bf16 v[20:23], v[156:159], v[220:223], v[20:23]
	v_mfma_f32_16x16x32_bf16 v[12:15], v[164:167], v[220:223], v[12:15]
	s_waitcnt lgkmcnt(0)
	v_mfma_f32_16x16x32_bf16 v[60:63], v[160:163], v[176:179], v[60:63]
	v_mfma_f32_16x16x32_bf16 v[56:59], v[168:171], v[176:179], v[56:59]
	v_mfma_f32_16x16x32_bf16 v[52:55], v[160:163], v[184:187], v[52:55]
	v_mfma_f32_16x16x32_bf16 v[44:47], v[168:171], v[184:187], v[44:47]
	v_mfma_f32_16x16x32_bf16 v[36:39], v[160:163], v[216:219], v[36:39]
	v_mfma_f32_16x16x32_bf16 v[28:31], v[168:171], v[216:219], v[28:31]
	v_mfma_f32_16x16x32_bf16 v[20:23], v[160:163], v[224:227], v[20:23]
	v_mfma_f32_16x16x32_bf16 v[12:15], v[168:171], v[224:227], v[12:15]
	s_barrier
	s_add_u32 s12, s12, s58
	s_addc_u32 s13, s13, 0
	s_add_i32 s41, s42, s19
	v_lshl_add_u64 v[250:251], s[12:13], 0, v[132:133]
	s_mov_b32 m0, s41
	v_lshl_add_u64 v[252:253], s[12:13], 0, v[128:129]
	global_load_lds_dwordx4 v132, s[12:13]
	s_add_i32 m0, s41, 0x2000
	s_nop 0
	global_load_lds_dwordx4 v128, s[12:13]
	v_add_u32_e32 v168, 0x18000, v154
	ds_read_b128 v[156:159], v168
	ds_read_b128 v[160:163], v168 offset:1024
	ds_read_b128 v[164:167], v168 offset:2048
	ds_read_b128 v[168:171], v168 offset:3072
	s_waitcnt vmcnt(10)
	s_barrier
	v_mfma_f32_16x16x32_bf16 v[48:51], v[228:231], v[172:175], v[48:51]
	v_mfma_f32_16x16x32_bf16 v[40:43], v[236:239], v[172:175], v[40:43]
	v_mfma_f32_16x16x32_bf16 v[32:35], v[228:231], v[180:183], v[32:35]
	v_mfma_f32_16x16x32_bf16 v[24:27], v[236:239], v[180:183], v[24:27]
	v_mfma_f32_16x16x32_bf16 v[16:19], v[228:231], v[188:191], v[16:19]
	v_mfma_f32_16x16x32_bf16 v[8:11], v[236:239], v[188:191], v[8:11]
	v_mfma_f32_16x16x32_bf16 v[4:7], v[228:231], v[220:223], v[4:7]
	v_mfma_f32_16x16x32_bf16 v[0:3], v[236:239], v[220:223], v[0:3]
	v_mfma_f32_16x16x32_bf16 v[48:51], v[232:235], v[176:179], v[48:51]
	v_mfma_f32_16x16x32_bf16 v[40:43], v[240:243], v[176:179], v[40:43]
	v_mfma_f32_16x16x32_bf16 v[32:35], v[232:235], v[184:187], v[32:35]
	v_mfma_f32_16x16x32_bf16 v[24:27], v[240:243], v[184:187], v[24:27]
	v_mfma_f32_16x16x32_bf16 v[16:19], v[232:235], v[216:219], v[16:19]
	v_mfma_f32_16x16x32_bf16 v[8:11], v[240:243], v[216:219], v[8:11]
	v_mfma_f32_16x16x32_bf16 v[4:7], v[232:235], v[224:227], v[4:7]
	v_mfma_f32_16x16x32_bf16 v[0:3], v[240:243], v[224:227], v[0:3]
	s_barrier
	s_add_i32 s12, 0, 0x18000
	s_add_u32 s10, s10, s58
	s_addc_u32 s11, s11, 0
	s_mov_b32 m0, s24
	ds_read_b128 v[172:175], v155 offset:32768
	ds_read_b128 v[180:183], v155 offset:34816
	ds_read_b128 v[188:191], v155 offset:36864
	ds_read_b128 v[220:223], v155 offset:38912
	ds_read_b128 v[176:179], v155 offset:33792
	ds_read_b128 v[184:187], v155 offset:35840
	ds_read_b128 v[216:219], v155 offset:37888
	ds_read_b128 v[224:227], v155 offset:39936
	global_load_lds_dwordx4 v132, s[10:11]
	s_mov_b32 m0, s25
	s_nop 0
	global_load_lds_dwordx4 v128, s[10:11]
	s_waitcnt lgkmcnt(8)
	s_waitcnt vmcnt(10)
	s_barrier
	s_waitcnt lgkmcnt(4)
	v_mfma_f32_16x16x32_bf16 v[124:127], v[156:159], v[172:175], v[124:127]
	v_mfma_f32_16x16x32_bf16 v[120:123], v[164:167], v[172:175], v[120:123]
	v_mfma_f32_16x16x32_bf16 v[116:119], v[156:159], v[180:183], v[116:119]
	v_mfma_f32_16x16x32_bf16 v[108:111], v[164:167], v[180:183], v[108:111]
	v_mfma_f32_16x16x32_bf16 v[100:103], v[156:159], v[188:191], v[100:103]
	v_mfma_f32_16x16x32_bf16 v[92:95], v[164:167], v[188:191], v[92:95]
	v_mfma_f32_16x16x32_bf16 v[84:87], v[156:159], v[220:223], v[84:87]
	v_mfma_f32_16x16x32_bf16 v[76:79], v[164:167], v[220:223], v[76:79]
	s_waitcnt lgkmcnt(0)
	v_mfma_f32_16x16x32_bf16 v[124:127], v[160:163], v[176:179], v[124:127]
	v_mfma_f32_16x16x32_bf16 v[120:123], v[168:171], v[176:179], v[120:123]
	v_mfma_f32_16x16x32_bf16 v[116:119], v[160:163], v[184:187], v[116:119]
	v_mfma_f32_16x16x32_bf16 v[108:111], v[168:171], v[184:187], v[108:111]
	v_mfma_f32_16x16x32_bf16 v[100:103], v[160:163], v[216:219], v[100:103]
	v_mfma_f32_16x16x32_bf16 v[92:95], v[168:171], v[216:219], v[92:95]
	v_mfma_f32_16x16x32_bf16 v[84:87], v[160:163], v[224:227], v[84:87]
	v_mfma_f32_16x16x32_bf16 v[76:79], v[168:171], v[224:227], v[76:79]
	s_barrier
	s_add_i32 s10, 0, 0x1c000
	s_add_i32 s11, s12, s19
	v_add_u32_e32 v200, s10, v154
	v_lshl_add_u64 v[152:153], v[152:153], 0, s[66:67]
	s_mov_b32 m0, s11
	ds_read_b128 v[228:231], v200
	ds_read_b128 v[236:239], v200 offset:2048
	ds_read_b128 v[232:235], v200 offset:1024
	ds_read_b128 v[240:243], v200 offset:3072
	global_load_lds_dwordx4 v[152:153], off
	v_lshl_add_u64 v[152:153], v[244:245], 0, s[66:67]
	s_add_i32 m0, s11, 0x2000
	s_nop 0
	global_load_lds_dwordx4 v[152:153], off
	s_waitcnt vmcnt(10)
	s_barrier
	s_waitcnt lgkmcnt(2)
	v_mfma_f32_16x16x32_bf16 v[112:115], v[228:231], v[172:175], v[112:115]
	v_mfma_f32_16x16x32_bf16 v[104:107], v[236:239], v[172:175], v[104:107]
	v_mfma_f32_16x16x32_bf16 v[96:99], v[228:231], v[180:183], v[96:99]
	v_mfma_f32_16x16x32_bf16 v[88:91], v[236:239], v[180:183], v[88:91]
	v_mfma_f32_16x16x32_bf16 v[80:83], v[228:231], v[188:191], v[80:83]
	v_mfma_f32_16x16x32_bf16 v[72:75], v[236:239], v[188:191], v[72:75]
	v_mfma_f32_16x16x32_bf16 v[68:71], v[228:231], v[220:223], v[68:71]
	v_mfma_f32_16x16x32_bf16 v[64:67], v[236:239], v[220:223], v[64:67]
	s_waitcnt lgkmcnt(0)
	v_mfma_f32_16x16x32_bf16 v[112:115], v[232:235], v[176:179], v[112:115]
	v_mfma_f32_16x16x32_bf16 v[104:107], v[240:243], v[176:179], v[104:107]
	v_mfma_f32_16x16x32_bf16 v[96:99], v[232:235], v[184:187], v[96:99]
	v_mfma_f32_16x16x32_bf16 v[88:91], v[240:243], v[184:187], v[88:91]
	v_mfma_f32_16x16x32_bf16 v[80:83], v[232:235], v[216:219], v[80:83]
	v_mfma_f32_16x16x32_bf16 v[72:75], v[240:243], v[216:219], v[72:75]
	v_mfma_f32_16x16x32_bf16 v[68:71], v[232:235], v[224:227], v[68:71]
	v_mfma_f32_16x16x32_bf16 v[64:67], v[240:243], v[224:227], v[64:67]
	s_barrier
	s_mov_b32 m0, s26
	v_lshl_add_u64 v[152:153], v[246:247], 0, s[66:67]
	ds_read_b128 v[172:175], v155 offset:49152
	ds_read_b128 v[180:183], v155 offset:51200
	ds_read_b128 v[188:191], v155 offset:53248
	ds_read_b128 v[220:223], v155 offset:55296
	ds_read_b128 v[176:179], v155 offset:50176
	ds_read_b128 v[184:187], v155 offset:52224
	ds_read_b128 v[216:219], v155 offset:54272
	ds_read_b128 v[224:227], v155 offset:56320
	global_load_lds_dwordx4 v[152:153], off
	v_lshl_add_u64 v[152:153], v[248:249], 0, s[66:67]
	s_mov_b32 m0, s27
	s_nop 0
	global_load_lds_dwordx4 v[152:153], off
	s_waitcnt vmcnt(10)
	s_barrier
	s_waitcnt lgkmcnt(4)
	v_mfma_f32_16x16x32_bf16 v[60:63], v[156:159], v[172:175], v[60:63]
	v_mfma_f32_16x16x32_bf16 v[56:59], v[164:167], v[172:175], v[56:59]
	v_mfma_f32_16x16x32_bf16 v[52:55], v[156:159], v[180:183], v[52:55]
	v_mfma_f32_16x16x32_bf16 v[44:47], v[164:167], v[180:183], v[44:47]
	v_mfma_f32_16x16x32_bf16 v[36:39], v[156:159], v[188:191], v[36:39]
	v_mfma_f32_16x16x32_bf16 v[28:31], v[164:167], v[188:191], v[28:31]
	v_mfma_f32_16x16x32_bf16 v[20:23], v[156:159], v[220:223], v[20:23]
	v_mfma_f32_16x16x32_bf16 v[12:15], v[164:167], v[220:223], v[12:15]
	s_waitcnt lgkmcnt(0)
	v_mfma_f32_16x16x32_bf16 v[60:63], v[160:163], v[176:179], v[60:63]
	v_mfma_f32_16x16x32_bf16 v[56:59], v[168:171], v[176:179], v[56:59]
	v_mfma_f32_16x16x32_bf16 v[52:55], v[160:163], v[184:187], v[52:55]
	v_mfma_f32_16x16x32_bf16 v[44:47], v[168:171], v[184:187], v[44:47]
	v_mfma_f32_16x16x32_bf16 v[36:39], v[160:163], v[216:219], v[36:39]
	v_mfma_f32_16x16x32_bf16 v[28:31], v[168:171], v[216:219], v[28:31]
	v_mfma_f32_16x16x32_bf16 v[20:23], v[160:163], v[224:227], v[20:23]
	v_mfma_f32_16x16x32_bf16 v[12:15], v[168:171], v[224:227], v[12:15]
	s_barrier
	s_add_i32 s10, s10, s19
	v_lshl_add_u64 v[152:153], v[250:251], 0, s[66:67]
	s_mov_b32 m0, s10
	s_nop 0
	global_load_lds_dwordx4 v[152:153], off
	v_lshl_add_u64 v[152:153], v[252:253], 0, s[66:67]
	s_add_i32 m0, s10, 0x2000
	s_nop 0
	global_load_lds_dwordx4 v[152:153], off
	v_add_u32_e32 v168, 0x10000, v154
	ds_read_b128 v[156:159], v168
	ds_read_b128 v[160:163], v168 offset:1024
	ds_read_b128 v[164:167], v168 offset:2048
	ds_read_b128 v[168:171], v168 offset:3072
	s_waitcnt vmcnt(10)
	s_barrier
	v_mfma_f32_16x16x32_bf16 v[48:51], v[228:231], v[172:175], v[48:51]
	v_mfma_f32_16x16x32_bf16 v[40:43], v[236:239], v[172:175], v[40:43]
	v_mfma_f32_16x16x32_bf16 v[32:35], v[228:231], v[180:183], v[32:35]
	v_mfma_f32_16x16x32_bf16 v[24:27], v[236:239], v[180:183], v[24:27]
	v_mfma_f32_16x16x32_bf16 v[16:19], v[228:231], v[188:191], v[16:19]
	v_mfma_f32_16x16x32_bf16 v[8:11], v[236:239], v[188:191], v[8:11]
	v_mfma_f32_16x16x32_bf16 v[4:7], v[228:231], v[220:223], v[4:7]
	v_mfma_f32_16x16x32_bf16 v[0:3], v[236:239], v[220:223], v[0:3]
	v_mfma_f32_16x16x32_bf16 v[48:51], v[232:235], v[176:179], v[48:51]
	v_mfma_f32_16x16x32_bf16 v[40:43], v[240:243], v[176:179], v[40:43]
	v_mfma_f32_16x16x32_bf16 v[32:35], v[232:235], v[184:187], v[32:35]
	v_mfma_f32_16x16x32_bf16 v[24:27], v[240:243], v[184:187], v[24:27]
	v_mfma_f32_16x16x32_bf16 v[16:19], v[232:235], v[216:219], v[16:19]
	v_mfma_f32_16x16x32_bf16 v[8:11], v[240:243], v[216:219], v[8:11]
	v_mfma_f32_16x16x32_bf16 v[4:7], v[232:235], v[224:227], v[4:7]
	v_mfma_f32_16x16x32_bf16 v[0:3], v[240:243], v[224:227], v[0:3]
	s_barrier
	s_add_u32 s8, s8, 0x100
	s_addc_u32 s9, s9, 0
	s_add_u32 s38, s38, 0x100
	s_addc_u32 s39, s39, 0
	s_cmp_ge_u32 s40, s28
	s_mov_b32 s10, s40
	s_cbranch_scc0 .LBB0_1234
	s_waitcnt lgkmcnt(0)
	v_mov_b32_e32 v152, v135
	s_mov_b64 s[8:9], s[0:1]
	v_readfirstlane_b32 s10, v152
	s_ashr_i32 s12, s10, 2
	s_load_dwordx2 s[8:9], s[8:9], 0x88
	s_lshl_b32 s11, s36, 8
	s_andn2_b32 s12, s12, 63
	s_lshr_b32 s10, s10, 1
	s_add_i32 s12, s12, s11
	s_lshl_b32 s11, s37, 8
	s_and_b32 s10, s10, 0x60
	v_and_or_b32 v156, v152, 15, s12
	s_or_b32 s10, s10, s11
	v_lshrrev_b32_e32 v152, 1, v152
	v_and_or_b32 v152, v152, 24, s10
	v_ashrrev_i32_e32 v153, 31, v152
	s_waitcnt lgkmcnt(0)
	v_lshl_add_u64 v[152:153], v[152:153], 1, s[8:9]
	s_mov_b64 s[8:9], 0x62a4400
	v_ashrrev_i32_e32 v157, 31, v156
	v_lshl_add_u64 v[158:159], v[152:153], 0, s[8:9]
	v_lshlrev_b64 v[152:153], 11, v[156:157]
	v_lshl_add_u64 v[152:153], v[158:159], 0, v[152:153]
	s_mov_b64 s[8:9], 0x40000
	v_cvt_pk_bf16_f32 v68, v68, v69
	v_cvt_pk_bf16_f32 v69, v70, v71
	v_cvt_pk_bf16_f32 v70, v64, v65
	v_lshl_add_u64 v[64:65], v[152:153], 0, s[8:9]
	s_mov_b32 s8, 0x40000
	v_cvt_pk_bf16_f32 v60, v60, v61
	v_cvt_pk_bf16_f32 v61, v62, v63
	v_cvt_pk_bf16_f32 v62, v56, v57
	v_add_co_u32_e32 v56, vcc, s8, v152
	v_cvt_pk_bf16_f32 v48, v48, v49
	v_cvt_pk_bf16_f32 v49, v50, v51
	s_mov_b64 s[8:9], 0x48000
	s_nop 0
	v_addc_co_u32_e32 v57, vcc, 0, v153, vcc
	v_cvt_pk_bf16_f32 v50, v40, v41
	v_cvt_pk_bf16_f32 v51, v42, v43
	global_store_dwordx4 v[64:65], v[48:51], off offset:256 sc1
	v_cvt_pk_bf16_f32 v42, v44, v45
	v_cvt_pk_bf16_f32 v32, v32, v33
	v_cvt_pk_bf16_f32 v33, v34, v35
	v_cvt_pk_bf16_f32 v112, v112, v113
	v_cvt_pk_bf16_f32 v113, v114, v115
	s_nop 1
	v_lshl_add_u64 v[48:49], v[152:153], 0, s[8:9]
	s_mov_b32 s8, 0x48000
	v_add_co_u32_e32 v44, vcc, s8, v152
	s_mov_b64 s[8:9], 0x50000
	v_cvt_pk_bf16_f32 v114, v104, v105
	v_or_b32_e32 v104, 16, v156
	v_addc_co_u32_e32 v45, vcc, 0, v153, vcc
	v_cvt_pk_bf16_f32 v34, v24, v25
	v_cvt_pk_bf16_f32 v35, v26, v27
	global_store_dwordx4 v[48:49], v[32:35], off offset:256 sc1
	v_ashrrev_i32_e32 v105, 31, v104
	v_cvt_pk_bf16_f32 v96, v96, v97
	v_cvt_pk_bf16_f32 v97, v98, v99
	v_cvt_pk_bf16_f32 v98, v88, v89
	v_or_b32_e32 v88, 32, v156
	v_lshl_add_u64 v[32:33], v[152:153], 0, s[8:9]
	s_mov_b32 s8, 0x50000
	v_cvt_pk_bf16_f32 v26, v28, v29
	v_add_co_u32_e32 v28, vcc, s8, v152
	v_cvt_pk_bf16_f32 v16, v16, v17
	v_cvt_pk_bf16_f32 v17, v18, v19
	s_mov_b64 s[8:9], 0x58000
	v_lshlrev_b64 v[104:105], 11, v[104:105]
	v_ashrrev_i32_e32 v89, 31, v88
	v_cvt_pk_bf16_f32 v80, v80, v81
	v_cvt_pk_bf16_f32 v81, v82, v83
	v_cvt_pk_bf16_f32 v82, v72, v73
	v_or_b32_e32 v72, 48, v156
	v_addc_co_u32_e32 v29, vcc, 0, v153, vcc
	v_cvt_pk_bf16_f32 v18, v8, v9
	v_cvt_pk_bf16_f32 v19, v10, v11
	global_store_dwordx4 v[32:33], v[16:19], off offset:256 sc1
	v_cvt_pk_bf16_f32 v115, v106, v107
	global_store_dwordx4 v[152:153], v[112:115], off offset:256 sc1
	v_lshlrev_b64 v[88:89], 11, v[88:89]
	v_lshl_add_u64 v[16:17], v[152:153], 0, s[8:9]
	s_mov_b32 s8, 0x58000
	v_lshl_add_u64 v[112:113], v[158:159], 0, v[104:105]
	v_ashrrev_i32_e32 v73, 31, v72
	v_cvt_pk_bf16_f32 v10, v12, v13
	v_add_co_u32_e32 v12, vcc, s8, v152
	v_cvt_pk_bf16_f32 v99, v90, v91
	global_store_dwordx4 v[112:113], v[96:99], off offset:256 sc1
	v_lshlrev_b64 v[72:73], 11, v[72:73]
	v_addc_co_u32_e32 v13, vcc, 0, v153, vcc
	v_lshl_add_u64 v[96:97], v[158:159], 0, v[88:89]
	v_cvt_pk_bf16_f32 v83, v74, v75
	global_store_dwordx4 v[96:97], v[80:83], off offset:256 sc1
	s_and_b64 vcc, exec, s[4:5]
	s_mov_b32 s37, s34
	v_lshl_add_u64 v[80:81], v[158:159], 0, v[72:73]
	s_mov_b32 s36, s35
	s_mov_b64 s[10:11], s[6:7]
	s_mov_b64 s[12:13], s[2:3]
	v_cvt_pk_bf16_f32 v124, v124, v125
	v_cvt_pk_bf16_f32 v125, v126, v127
	v_cvt_pk_bf16_f32 v126, v120, v121
	v_cvt_pk_bf16_f32 v127, v122, v123
	global_store_dwordx4 v[152:153], v[124:127], off sc1
	v_cvt_pk_bf16_f32 v104, v116, v117
	v_cvt_pk_bf16_f32 v105, v118, v119
	v_cvt_pk_bf16_f32 v106, v108, v109
	v_cvt_pk_bf16_f32 v107, v110, v111
	global_store_dwordx4 v[112:113], v[104:107], off sc1
	v_cvt_pk_bf16_f32 v88, v100, v101
	v_cvt_pk_bf16_f32 v89, v102, v103
	v_cvt_pk_bf16_f32 v90, v92, v93
	v_cvt_pk_bf16_f32 v91, v94, v95
	global_store_dwordx4 v[96:97], v[88:91], off sc1
	v_cvt_pk_bf16_f32 v72, v84, v85
	v_cvt_pk_bf16_f32 v73, v86, v87
	v_cvt_pk_bf16_f32 v74, v76, v77
	v_cvt_pk_bf16_f32 v75, v78, v79
	global_store_dwordx4 v[80:81], v[72:75], off sc1
	v_cvt_pk_bf16_f32 v71, v66, v67
	global_store_dwordx4 v[80:81], v[68:71], off offset:256 sc1
	v_cvt_pk_bf16_f32 v63, v58, v59
	global_store_dwordx4 v[56:57], v[60:63], off sc1
	v_cvt_pk_bf16_f32 v40, v52, v53
	v_cvt_pk_bf16_f32 v41, v54, v55
	v_cvt_pk_bf16_f32 v43, v46, v47
	global_store_dwordx4 v[44:45], v[40:43], off sc1
	v_cvt_pk_bf16_f32 v24, v36, v37
	v_cvt_pk_bf16_f32 v25, v38, v39
	v_cvt_pk_bf16_f32 v27, v30, v31
	global_store_dwordx4 v[28:29], v[24:27], off sc1
	v_cvt_pk_bf16_f32 v8, v20, v21
	v_cvt_pk_bf16_f32 v9, v22, v23
	v_cvt_pk_bf16_f32 v11, v14, v15
	global_store_dwordx4 v[12:13], v[8:11], off sc1
	v_cvt_pk_bf16_f32 v4, v4, v5
	v_cvt_pk_bf16_f32 v5, v6, v7
	v_cvt_pk_bf16_f32 v6, v0, v1
	v_cvt_pk_bf16_f32 v7, v2, v3
	global_store_dwordx4 v[16:17], v[4:7], off offset:256 sc1
	s_cbranch_vccz .LBB0_1223
	s_waitcnt vmcnt(0)
	s_cmpk_gt_u32 s14, 0xff
	s_cbranch_scc1 .LBB0_1238
	s_barrier
